# speedup vs baseline: 1.0109x; 1.0109x over previous
; __device__ __forceinline__ void qkt(f32x16& p0, f32x16& p1, const char* Ks, const bf16x8* qr, int r32, int hi) {
;     p0 = f32x16{}; p1 = f32x16{};
; #pragma unroll
;     for (int d0 = 0; d0 < 8; ++d0) { const int cb = (d0 * 16 + hi * 8) * 2;
;         bf16x8 b0 = *reinterpret_cast<const bf16x8*>(Ks + KSWZ(r32, cb));
;         bf16x8 b1 = *reinterpret_cast<const bf16x8*>(Ks + KSWZ(32 + r32, cb));
;         p0 = __builtin_amdgcn_mfma_f32_32x32x16_bf16(b0, qr[d0], p0, 0, 0, 0);
;         p1 = __builtin_amdgcn_mfma_f32_32x32x16_bf16(b1, qr[d0], p1, 0, 0, 0); }
; }
; template <int LDQ, int LDK, int LDV, int LDO>
; __device__ __forceinline__ void attn256_body(const int tid, const bf16_t* __restrict__ Qb, const bf16_t* __restrict__ Kh, const bf16_t* __restrict__ Vh, bf16_t* __restrict__ Ob, int seq, char* lds, LAS unsigned char* ldsl) {
;     ...
;     for (int j = 0; j < NT; ++j) {
;         const int b = j & 1;
;         asm volatile("s_waitcnt vmcnt(0)" ::: "memory"); __builtin_amdgcn_s_barrier(); asm volatile("" ::: "memory");
;         if (j + 1 < NT) A2_ISSUE(j + 1, b ^ 1);
;         f32x16 p0, p1;
;         qkt(p0, p1, lds + A2_KOFF + b * 16384, qr, r32, hi);
;         float pmax = p0[0];
; #pragma unroll
;         for (int r = 1; r < 16; ++r) pmax = fmaxf(pmax, p0[r]);
; #pragma unroll
;         for (int r = 0; r < 16; ++r) pmax = fmaxf(pmax, p1[r]);
;         { auto rr = __builtin_amdgcn_permlane32_swap(__float_as_uint(pmax), __float_as_uint(pmax), false, false); pmax = fmaxf(__uint_as_float(rr[0]), __uint_as_float(rr[1])); }
;         float alpha = 1.f;
;         if (!__all(pmax - m_reg <= ATT_THR / ATT_SCALE)) { const float mn = fmaxf(m_reg, pmax); alpha = __builtin_amdgcn_exp2f((m_reg - mn) * C); m_reg = mn; }
;         const float mnC = -m_reg * C;
;         float ps = 0.f;
; #pragma unroll
;         for (int r = 0; r < 16; ++r) { p0[r] = __builtin_amdgcn_exp2f(fmaf(p0[r], C, mnC)); p1[r] = __builtin_amdgcn_exp2f(fmaf(p1[r], C, mnC)); ps += p0[r] + p1[r]; }
;         { auto rr = __builtin_amdgcn_permlane32_swap(__float_as_uint(ps), __float_as_uint(ps), false, false); ps = __uint_as_float(rr[0]) + __uint_as_float(rr[1]); }
;         l_reg = l_reg * alpha + ps;
;         bf16x8 pa0, pa1, pa2, pa3;
;         PK4(p0, 0, pa0); PK4(p0, 8, pa1); PK4(p1, 0, pa2); PK4(p1, 8, pa3);
.LBB0_134:
	s_waitcnt vmcnt(0)
	s_barrier
	s_and_b32 s24, s23, 1
	s_lshl_b32 s6, s24, 14
	v_add3_u32 v240, s6, v212, v195
	ds_read_b128 v[224:227], v240
	v_add3_u32 v241, s6, v213, v195
	ds_read_b128 v[228:231], v241
	v_add3_u32 v240, s6, v214, v195
	ds_read_b128 v[232:235], v240
	v_add3_u32 v241, s6, v215, v195
	ds_read_b128 v[236:239], v241
	v_add3_u32 v240, s6, v216, v195
	ds_read_b128 v[244:247], v240
	v_add3_u32 v241, s6, v218, v195
	ds_read_b128 v[248:251], v241
	s_cmp_eq_u32 s23, 63
	s_cbranch_scc1 .Lattn_nodma
	s_xor_b32 s7, s6, 0x4000
	s_add_i32 s7, s21, s7
	v_lshl_add_u64 v[130:131], v[206:207], 0, s[0:1]
	s_mov_b32 m0, s7
	s_nop 0
	global_load_lds_dwordx4 v[130:131], off
	s_add_i32 m0, s7, 0x2000
	s_lshl_b32 s7, s24, 15
	s_xor_b32 s7, s7, 0x8000
	v_lshl_add_u64 v[130:131], v[204:205], 0, s[0:1]
	s_add_i32 s7, s21, s7
	global_load_lds_dwordx4 v[130:131], off
	s_add_i32 m0, s7, 0x8000
	v_lshl_add_u64 v[130:131], v[196:197], 0, s[0:1]
	global_load_lds_dwordx4 v[130:131], off
	v_lshl_add_u64 v[130:131], v[198:199], 0, s[0:1]
	s_add_i32 m0, s7, 0xa000
	s_nop 0
	global_load_lds_dwordx4 v[130:131], off
	v_lshl_add_u64 v[130:131], v[200:201], 0, s[0:1]
	s_add_i32 m0, s7, 0xc000
	s_nop 0
	global_load_lds_dwordx4 v[130:131], off
	v_lshl_add_u64 v[130:131], v[202:203], 0, s[0:1]
	s_add_i32 m0, s7, 0xe000
	s_nop 0
	global_load_lds_dwordx4 v[130:131], off
.Lattn_nodma:
	v_lshl_add_u32 v253, s24, 15, v221
	s_waitcnt lgkmcnt(5)
	v_mfma_f32_32x32x16_bf16 v[130:145], v[224:227], v[162:165], 0
	v_add3_u32 v240, s6, v219, v195
	ds_read_b128 v[224:227], v240
	s_waitcnt lgkmcnt(5)
	v_mfma_f32_32x32x16_bf16 v[130:145], v[228:231], v[166:169], v[130:145]
	v_add3_u32 v241, s6, v220, v195
	ds_read_b128 v[228:231], v241
	s_waitcnt lgkmcnt(5)
	v_mfma_f32_32x32x16_bf16 v[130:145], v[232:235], v[170:173], v[130:145]
	v_add3_u32 v240, s6, v212, v195
	ds_read_b128 v[232:235], v240 offset:8192
	s_waitcnt lgkmcnt(5)
	v_mfma_f32_32x32x16_bf16 v[130:145], v[236:239], v[174:177], v[130:145]
	v_add3_u32 v241, s6, v213, v195
	ds_read_b128 v[236:239], v241 offset:8192
	s_waitcnt lgkmcnt(5)
	v_mfma_f32_32x32x16_bf16 v[130:145], v[244:247], v[178:181], v[130:145]
	v_add3_u32 v240, s6, v214, v195
	ds_read_b128 v[244:247], v240 offset:8192
	s_waitcnt lgkmcnt(5)
	v_mfma_f32_32x32x16_bf16 v[130:145], v[248:251], v[182:185], v[130:145]
	v_add3_u32 v241, s6, v215, v195
	ds_read_b128 v[248:251], v241 offset:8192
	s_waitcnt lgkmcnt(5)
	v_mfma_f32_32x32x16_bf16 v[130:145], v[224:227], v[186:189], v[130:145]
	v_add3_u32 v240, s6, v216, v195
	ds_read_b128 v[224:227], v240 offset:8192
	s_waitcnt lgkmcnt(5)
	v_mfma_f32_32x32x16_bf16 v[130:145], v[228:231], v[190:193], v[130:145]
	v_add3_u32 v241, s6, v218, v195
	ds_read_b128 v[228:231], v241 offset:8192
	s_waitcnt lgkmcnt(5)
	v_mfma_f32_32x32x16_bf16 v[146:161], v[232:235], v[162:165], 0
	v_add3_u32 v240, s6, v219, v195
	ds_read_b128 v[232:235], v240 offset:8192
	s_waitcnt lgkmcnt(5)
	v_mfma_f32_32x32x16_bf16 v[146:161], v[236:239], v[166:169], v[146:161]
	v_add3_u32 v241, s6, v220, v195
	ds_read_b128 v[236:239], v241 offset:8192
	s_waitcnt lgkmcnt(5)
	v_mfma_f32_32x32x16_bf16 v[146:161], v[244:247], v[170:173], v[146:161]
	ds_read_b64_tr_b16 v[244:245], v253 offset:0
	ds_read_b64_tr_b16 v[246:247], v253 offset:0x800
	s_waitcnt lgkmcnt(6)
	v_mfma_f32_32x32x16_bf16 v[146:161], v[248:251], v[174:177], v[146:161]
	ds_read_b64_tr_b16 v[248:249], v253 offset:0x200
	ds_read_b64_tr_b16 v[250:251], v253 offset:0xa00
	v_max3_f32 v0, v130, v131, v132
	v_max3_f32 v0, v0, v133, v134
	s_waitcnt lgkmcnt(7)
	v_mfma_f32_32x32x16_bf16 v[146:161], v[224:227], v[178:181], v[146:161]
	ds_read_b64_tr_b16 v[224:225], v253 offset:0x400
	ds_read_b64_tr_b16 v[226:227], v253 offset:0xc00
	v_max3_f32 v0, v0, v135, v136
	v_max3_f32 v0, v0, v137, v138
	s_waitcnt lgkmcnt(8)
	v_mfma_f32_32x32x16_bf16 v[146:161], v[228:231], v[182:185], v[146:161]
	ds_read_b64_tr_b16 v[228:229], v253 offset:0x600
	ds_read_b64_tr_b16 v[230:231], v253 offset:0xe00
	v_max3_f32 v0, v0, v139, v140
	v_max3_f32 v0, v0, v141, v142
	s_waitcnt lgkmcnt(9)
	v_mfma_f32_32x32x16_bf16 v[146:161], v[232:235], v[186:189], v[146:161]
	ds_read_b64_tr_b16 v[232:233], v253 offset:0x4000
	ds_read_b64_tr_b16 v[234:235], v253 offset:0x4800
	v_max3_f32 v0, v0, v143, v144
	v_max_f32_e32 v0, v0, v145
	s_waitcnt lgkmcnt(10)
	v_mfma_f32_32x32x16_bf16 v[146:161], v[236:239], v[190:193], v[146:161]
	ds_read_b64_tr_b16 v[236:237], v253 offset:0x4200
	ds_read_b64_tr_b16 v[238:239], v253 offset:0x4a00
	v_lshl_add_u64 v[196:197], v[196:197], 0, s[80:81]
	v_lshl_add_u64 v[198:199], v[198:199], 0, s[80:81]
	v_lshl_add_u64 v[200:201], v[200:201], 0, s[80:81]
	v_lshl_add_u64 v[202:203], v[202:203], 0, s[80:81]
	v_lshl_add_u64 v[204:205], v[204:205], 0, s[82:83]
	v_lshl_add_u64 v[206:207], v[206:207], 0, s[82:83]
	s_add_i32 s23, s23, 1
	s_nop 2
	v_max3_f32 v0, v0, v146, v147
	v_max3_f32 v0, v0, v148, v149
	v_max3_f32 v0, v0, v150, v151
	v_max3_f32 v0, v0, v152, v153
	v_max3_f32 v0, v0, v154, v155
	v_max3_f32 v0, v0, v156, v157
	v_max3_f32 v0, v0, v158, v159
	v_max3_f32 v0, v0, v160, v161
	v_mov_b32_e32 v240, v0
	s_nop 1
	v_permlane32_swap_b32_e32 v0, v240
	v_max_f32_e32 v0, v0, v240
	v_sub_f32_e32 v240, v0, v222
	v_cmp_ge_f32_e32 vcc, 0x42b504f3, v240
	s_cmp_eq_u64 vcc, exec
	v_max_f32_e32 v0, v222, v0
	s_cselect_b64 vcc, -1, 0
	v_sub_f32_e32 v240, v222, v0
	v_cndmask_b32_e32 v222, v0, v222, vcc
	v_mul_f32_e32 v240, 0x3e0293ee, v240
	v_mul_f32_e32 v0, 0xbe0293ee, v222
	v_exp_f32_e32 v243, v240
	v_fmamk_f32 v130, v130, 0x3e0293ee, v0
	v_fmamk_f32 v131, v131, 0x3e0293ee, v0
	v_fmamk_f32 v132, v132, 0x3e0293ee, v0
	v_fmamk_f32 v133, v133, 0x3e0293ee, v0
	v_fmamk_f32 v134, v134, 0x3e0293ee, v0
	v_fmamk_f32 v135, v135, 0x3e0293ee, v0
	v_fmamk_f32 v136, v136, 0x3e0293ee, v0
	v_fmamk_f32 v137, v137, 0x3e0293ee, v0
	v_cndmask_b32_e64 v243, v243, 1.0, vcc
	v_cmp_gt_f32_e32 vcc, 1.0, v243
	s_cbranch_vccnz .Lattn_rescale
; #define SBAR() __builtin_amdgcn_sched_barrier(0)
; #define PV_MMA(OD, R) do { OD = __builtin_amdgcn_mfma_f32_32x32x16_bf16(pa0, PKF(R[0], R[1]), OD, 0, 0, 0); OD = __builtin_amdgcn_mfma_f32_32x32x16_bf16(pa1, PKF(R[2], R[3]), OD, 0, 0, 0); \
;         OD = __builtin_amdgcn_mfma_f32_32x32x16_bf16(pa2, PKF(R[4], R[5]), OD, 0, 0, 0); OD = __builtin_amdgcn_mfma_f32_32x32x16_bf16(pa3, PKF(R[6], R[7]), OD, 0, 0, 0); SBAR(); } while (0)
; #define PV_W8() do { asm volatile("s_waitcnt lgkmcnt(8)" ::: "memory"); SBAR(); } while (0)
; __device__ __forceinline__ void pv256(f32x16* o, int vb, bf16x8 pa0, bf16x8 pa1, bf16x8 pa2, bf16x8 pa3) {
;     s16x4 ra[8], rb[8];
;     asm volatile("s_waitcnt lgkmcnt(0)" ::: "memory");
;     PV_RD8(0, 0, ra);
;     PV_RD8(1, 0, rb); PV_W8(); PV_MMA(o[0], ra);
;     PV_RD8(2, 0, ra); PV_W8(); PV_MMA(o[1], rb);
;     PV_RD8(3, 0, rb); PV_W8(); PV_MMA(o[2], ra);
;     PV_RD8(0, 16384, ra); PV_W8(); PV_MMA(o[3], rb);
;     PV_RD8(1, 16384, rb); PV_W8(); PV_MMA(o[4], ra);
;     PV_RD8(2, 16384, ra); PV_W8(); PV_MMA(o[5], rb);
;     PV_RD8(3, 16384, rb); PV_W8(); PV_MMA(o[6], ra);
;     asm volatile("s_waitcnt lgkmcnt(0)" ::: "memory"); SBAR(); PV_MMA(o[7], rb);
; }
; template <int LDQ, int LDK, int LDV, int LDO>
; __device__ __forceinline__ void attn256_body(const int tid, const bf16_t* __restrict__ Qb, const bf16_t* __restrict__ Kh, const bf16_t* __restrict__ Vh, bf16_t* __restrict__ Ob, int seq, char* lds, LAS unsigned char* ldsl) {
;     ...
;         float ps = 0.f;
; #pragma unroll
;         for (int r = 0; r < 16; ++r) { p0[r] = __builtin_amdgcn_exp2f(fmaf(p0[r], C, mnC)); p1[r] = __builtin_amdgcn_exp2f(fmaf(p1[r], C, mnC)); ps += p0[r] + p1[r]; }
;         { auto rr = __builtin_amdgcn_permlane32_swap(__float_as_uint(ps), __float_as_uint(ps), false, false); ps = __uint_as_float(rr[0]) + __uint_as_float(rr[1]); }
;         l_reg = l_reg * alpha + ps;
;         bf16x8 pa0, pa1, pa2, pa3;
;         PK4(p0, 0, pa0); PK4(p0, 8, pa1); PK4(p1, 0, pa2); PK4(p1, 8, pa3);
.Lattn_resc_done:
	v_exp_f32_e32 v130, v130
	v_exp_f32_e32 v131, v131
	v_exp_f32_e32 v132, v132
	v_exp_f32_e32 v133, v133
	v_exp_f32_e32 v134, v134
	v_exp_f32_e32 v135, v135
	v_exp_f32_e32 v136, v136
	v_exp_f32_e32 v137, v137
	v_add_f32_e32 v252, v130, v131
	v_cvt_pk_bf16_f32 v130, v130, v131
	v_add_f32_e32 v208, v132, v133
	v_cvt_pk_bf16_f32 v131, v132, v133
	v_add_f32_e32 v209, v134, v135
	v_cvt_pk_bf16_f32 v132, v134, v135
	v_add_f32_e32 v240, v136, v137
	v_cvt_pk_bf16_f32 v133, v136, v137
	s_nop 0
	v_permlane32_swap_b32_e32 v130, v132
	v_permlane32_swap_b32_e32 v131, v133
	v_add_f32_e32 v252, v252, v208
	v_add_f32_e32 v209, v209, v240
	v_add_f32_e32 v252, v252, v209
	s_waitcnt lgkmcnt(10)
	v_mfma_f32_32x32x16_bf16 v[114:129], v[130:133], v[244:247], v[114:129]
	v_fmamk_f32 v138, v138, 0x3e0293ee, v0
	v_exp_f32_e32 v138, v138
	v_fmamk_f32 v139, v139, 0x3e0293ee, v0
	v_exp_f32_e32 v139, v139
	ds_read_b64_tr_b16 v[244:245], v253 offset:0x4400
	ds_read_b64_tr_b16 v[246:247], v253 offset:0x4c00
	s_waitcnt lgkmcnt(10)
	v_mfma_f32_32x32x16_bf16 v[98:113], v[130:133], v[248:251], v[98:113]
	v_add_f32_e32 v252, v252, v138
	v_fmamk_f32 v140, v140, 0x3e0293ee, v0
	v_exp_f32_e32 v140, v140
	v_add_f32_e32 v252, v252, v139
	v_fmamk_f32 v141, v141, 0x3e0293ee, v0
	ds_read_b64_tr_b16 v[248:249], v253 offset:0x4600
	ds_read_b64_tr_b16 v[250:251], v253 offset:0x4e00
	s_waitcnt lgkmcnt(10)
	v_mfma_f32_32x32x16_bf16 v[82:97], v[130:133], v[224:227], v[82:97]
	v_exp_f32_e32 v141, v141
	v_add_f32_e32 v252, v252, v140
	v_fmamk_f32 v142, v142, 0x3e0293ee, v0
	v_exp_f32_e32 v142, v142
	ds_read_b64_tr_b16 v[224:225], v253 offset:0x1000
	ds_read_b64_tr_b16 v[226:227], v253 offset:0x1800
	s_waitcnt lgkmcnt(10)
	v_mfma_f32_32x32x16_bf16 v[66:81], v[130:133], v[228:231], v[66:81]
	v_add_f32_e32 v252, v252, v141
	v_fmamk_f32 v143, v143, 0x3e0293ee, v0
	v_exp_f32_e32 v143, v143
	v_add_f32_e32 v252, v252, v142
	v_fmamk_f32 v144, v144, 0x3e0293ee, v0
	ds_read_b64_tr_b16 v[228:229], v253 offset:0x1200
	ds_read_b64_tr_b16 v[230:231], v253 offset:0x1a00
	s_waitcnt lgkmcnt(10)
	v_mfma_f32_32x32x16_bf16 v[50:65], v[130:133], v[232:235], v[50:65]
	v_exp_f32_e32 v144, v144
	v_add_f32_e32 v252, v252, v143
	v_fmamk_f32 v145, v145, 0x3e0293ee, v0
	v_exp_f32_e32 v145, v145
	ds_read_b64_tr_b16 v[232:233], v253 offset:0x1400
	ds_read_b64_tr_b16 v[234:235], v253 offset:0x1c00
	s_waitcnt lgkmcnt(10)
	v_mfma_f32_32x32x16_bf16 v[34:49], v[130:133], v[236:239], v[34:49]
	v_add_f32_e32 v252, v252, v144
	v_cvt_pk_bf16_f32 v134, v138, v139
	v_add_f32_e32 v252, v252, v145
	v_cvt_pk_bf16_f32 v135, v140, v141
	v_cvt_pk_bf16_f32 v136, v142, v143
	v_cvt_pk_bf16_f32 v137, v144, v145
	ds_read_b64_tr_b16 v[236:237], v253 offset:0x1600
	ds_read_b64_tr_b16 v[238:239], v253 offset:0x1e00
	s_waitcnt lgkmcnt(10)
	v_mfma_f32_32x32x16_bf16 v[18:33], v[130:133], v[244:247], v[18:33]
	s_nop 0
	v_permlane32_swap_b32_e32 v134, v136
	v_permlane32_swap_b32_e32 v135, v137
	v_fmamk_f32 v146, v146, 0x3e0293ee, v0
	v_exp_f32_e32 v146, v146
	ds_read_b64_tr_b16 v[244:245], v253 offset:0x5000
	ds_read_b64_tr_b16 v[246:247], v253 offset:0x5800
	s_waitcnt lgkmcnt(10)
	v_mfma_f32_32x32x16_bf16 v[2:17], v[130:133], v[248:251], v[2:17]
	v_fmamk_f32 v147, v147, 0x3e0293ee, v0
	v_exp_f32_e32 v147, v147
	v_add_f32_e32 v252, v252, v146
	v_fmamk_f32 v148, v148, 0x3e0293ee, v0
	ds_read_b64_tr_b16 v[248:249], v253 offset:0x5200
	ds_read_b64_tr_b16 v[250:251], v253 offset:0x5a00
	s_waitcnt lgkmcnt(10)
	v_mfma_f32_32x32x16_bf16 v[114:129], v[134:137], v[224:227], v[114:129]
	v_exp_f32_e32 v148, v148
	v_add_f32_e32 v252, v252, v147
	v_fmamk_f32 v149, v149, 0x3e0293ee, v0
	v_exp_f32_e32 v149, v149
	ds_read_b64_tr_b16 v[224:225], v253 offset:0x5400
	ds_read_b64_tr_b16 v[226:227], v253 offset:0x5c00
	s_waitcnt lgkmcnt(10)
	v_mfma_f32_32x32x16_bf16 v[98:113], v[134:137], v[228:231], v[98:113]
	v_add_f32_e32 v252, v252, v148
	v_fmamk_f32 v150, v150, 0x3e0293ee, v0
	v_exp_f32_e32 v150, v150
	v_add_f32_e32 v252, v252, v149
	v_fmamk_f32 v151, v151, 0x3e0293ee, v0
	ds_read_b64_tr_b16 v[228:229], v253 offset:0x5600
	ds_read_b64_tr_b16 v[230:231], v253 offset:0x5e00
	s_waitcnt lgkmcnt(10)
	v_mfma_f32_32x32x16_bf16 v[82:97], v[134:137], v[232:235], v[82:97]
	v_exp_f32_e32 v151, v151
	v_add_f32_e32 v252, v252, v150
	v_fmamk_f32 v152, v152, 0x3e0293ee, v0
	v_exp_f32_e32 v152, v152
	ds_read_b64_tr_b16 v[232:233], v253 offset:0x2000
	ds_read_b64_tr_b16 v[234:235], v253 offset:0x2800
	s_waitcnt lgkmcnt(10)
	v_mfma_f32_32x32x16_bf16 v[66:81], v[134:137], v[236:239], v[66:81]
	v_add_f32_e32 v252, v252, v151
	v_fmamk_f32 v153, v153, 0x3e0293ee, v0
	v_exp_f32_e32 v153, v153
	v_add_f32_e32 v252, v252, v152
	v_cvt_pk_bf16_f32 v138, v146, v147
	ds_read_b64_tr_b16 v[236:237], v253 offset:0x2200
	ds_read_b64_tr_b16 v[238:239], v253 offset:0x2a00
	s_waitcnt lgkmcnt(10)
	v_mfma_f32_32x32x16_bf16 v[50:65], v[134:137], v[244:247], v[50:65]
	v_add_f32_e32 v252, v252, v153
	v_cvt_pk_bf16_f32 v139, v148, v149
	v_cvt_pk_bf16_f32 v140, v150, v151
	v_cvt_pk_bf16_f32 v141, v152, v153
	s_nop 0
	v_permlane32_swap_b32_e32 v138, v140
	ds_read_b64_tr_b16 v[244:245], v253 offset:0x2400
	ds_read_b64_tr_b16 v[246:247], v253 offset:0x2c00
	s_waitcnt lgkmcnt(10)
	v_mfma_f32_32x32x16_bf16 v[34:49], v[134:137], v[248:251], v[34:49]
	v_permlane32_swap_b32_e32 v139, v141
	v_fmamk_f32 v154, v154, 0x3e0293ee, v0
	v_exp_f32_e32 v154, v154
	v_fmamk_f32 v155, v155, 0x3e0293ee, v0
	ds_read_b64_tr_b16 v[248:249], v253 offset:0x2600
	ds_read_b64_tr_b16 v[250:251], v253 offset:0x2e00
	s_waitcnt lgkmcnt(10)
; __device__ __forceinline__ int crow(int r, int hi) { return (r & 3) + 8 * (r >> 2) + 4 * hi; }
; #define SBAR() __builtin_amdgcn_sched_barrier(0)
; #define PV_MMA(OD, R) do { OD = __builtin_amdgcn_mfma_f32_32x32x16_bf16(pa0, PKF(R[0], R[1]), OD, 0, 0, 0); OD = __builtin_amdgcn_mfma_f32_32x32x16_bf16(pa1, PKF(R[2], R[3]), OD, 0, 0, 0); \
;         OD = __builtin_amdgcn_mfma_f32_32x32x16_bf16(pa2, PKF(R[4], R[5]), OD, 0, 0, 0); OD = __builtin_amdgcn_mfma_f32_32x32x16_bf16(pa3, PKF(R[6], R[7]), OD, 0, 0, 0); SBAR(); } while (0)
; __device__ __forceinline__ void pv256(f32x16* o, int vb, bf16x8 pa0, bf16x8 pa1, bf16x8 pa2, bf16x8 pa3) {
;     s16x4 ra[8], rb[8];
;     asm volatile("s_waitcnt lgkmcnt(0)" ::: "memory");
;     PV_RD8(0, 0, ra);
;     PV_RD8(1, 0, rb); PV_W8(); PV_MMA(o[0], ra);
;     PV_RD8(2, 0, ra); PV_W8(); PV_MMA(o[1], rb);
;     PV_RD8(3, 0, rb); PV_W8(); PV_MMA(o[2], ra);
;     PV_RD8(0, 16384, ra); PV_W8(); PV_MMA(o[3], rb);
;     PV_RD8(1, 16384, rb); PV_W8(); PV_MMA(o[4], ra);
;     PV_RD8(2, 16384, ra); PV_W8(); PV_MMA(o[5], rb);
;     PV_RD8(3, 16384, rb); PV_W8(); PV_MMA(o[6], ra);
;     asm volatile("s_waitcnt lgkmcnt(0)" ::: "memory"); SBAR(); PV_MMA(o[7], rb);
; }
; template <int LDQ, int LDK, int LDV, int LDO>
; __device__ __forceinline__ void attn256_body(const int tid, const bf16_t* __restrict__ Qb, const bf16_t* __restrict__ Kh, const bf16_t* __restrict__ Vh, bf16_t* __restrict__ Ob, int seq, char* lds, LAS unsigned char* ldsl) {
;     ...
;         for (int r = 0; r < 16; ++r) { p0[r] = __builtin_amdgcn_exp2f(fmaf(p0[r], C, mnC)); p1[r] = __builtin_amdgcn_exp2f(fmaf(p1[r], C, mnC)); ps += p0[r] + p1[r]; }
;         { auto rr = __builtin_amdgcn_permlane32_swap(__float_as_uint(ps), __float_as_uint(ps), false, false); ps = __uint_as_float(rr[0]) + __uint_as_float(rr[1]); }
;         l_reg = l_reg * alpha + ps;
;         bf16x8 pa0, pa1, pa2, pa3;
;         PK4(p0, 0, pa0); PK4(p0, 8, pa1); PK4(p1, 0, pa2); PK4(p1, 8, pa3);
;         if (__any(alpha < 1.f)) { if (hi == 0) al_l[r32] = alpha; asm volatile("s_waitcnt lgkmcnt(0)" ::: "memory");
; #pragma unroll
;             for (int r = 0; r < 16; ++r) { const float f = al_l[crow(r, hi)];
; #pragma unroll
;                 for (int d = 0; d < 8; ++d) o[d][r] *= f; } }
;         const int vb = vb0 + b * 32768;
;         pv256(o, vb, pa0, pa1, pa2, pa3);
	v_mfma_f32_32x32x16_bf16 v[18:33], v[134:137], v[224:227], v[18:33]
	v_exp_f32_e32 v155, v155
	v_add_f32_e32 v252, v252, v154
	v_fmamk_f32 v156, v156, 0x3e0293ee, v0
	v_exp_f32_e32 v156, v156
	ds_read_b64_tr_b16 v[224:225], v253 offset:0x6000
	ds_read_b64_tr_b16 v[226:227], v253 offset:0x6800
	s_waitcnt lgkmcnt(10)
	v_mfma_f32_32x32x16_bf16 v[2:17], v[134:137], v[228:231], v[2:17]
	v_add_f32_e32 v252, v252, v155
	v_fmamk_f32 v157, v157, 0x3e0293ee, v0
	v_exp_f32_e32 v157, v157
	v_add_f32_e32 v252, v252, v156
	v_fmamk_f32 v158, v158, 0x3e0293ee, v0
	ds_read_b64_tr_b16 v[228:229], v253 offset:0x6200
	ds_read_b64_tr_b16 v[230:231], v253 offset:0x6a00
	s_waitcnt lgkmcnt(10)
	v_mfma_f32_32x32x16_bf16 v[114:129], v[138:141], v[232:235], v[114:129]
	v_exp_f32_e32 v158, v158
	v_add_f32_e32 v252, v252, v157
	v_fmamk_f32 v159, v159, 0x3e0293ee, v0
	v_exp_f32_e32 v159, v159
	ds_read_b64_tr_b16 v[232:233], v253 offset:0x6400
	ds_read_b64_tr_b16 v[234:235], v253 offset:0x6c00
	s_waitcnt lgkmcnt(10)
	v_mfma_f32_32x32x16_bf16 v[98:113], v[138:141], v[236:239], v[98:113]
	v_add_f32_e32 v252, v252, v158
	v_fmamk_f32 v160, v160, 0x3e0293ee, v0
	v_exp_f32_e32 v160, v160
	v_add_f32_e32 v252, v252, v159
	v_fmamk_f32 v161, v161, 0x3e0293ee, v0
	ds_read_b64_tr_b16 v[236:237], v253 offset:0x6600
	ds_read_b64_tr_b16 v[238:239], v253 offset:0x6e00
	s_waitcnt lgkmcnt(10)
	v_mfma_f32_32x32x16_bf16 v[82:97], v[138:141], v[244:247], v[82:97]
	v_exp_f32_e32 v161, v161
	v_add_f32_e32 v252, v252, v160
	v_cvt_pk_bf16_f32 v142, v154, v155
	v_add_f32_e32 v252, v252, v161
	v_cvt_pk_bf16_f32 v143, v156, v157
	ds_read_b64_tr_b16 v[244:245], v253 offset:0x3000
	ds_read_b64_tr_b16 v[246:247], v253 offset:0x3800
	s_waitcnt lgkmcnt(10)
	v_mfma_f32_32x32x16_bf16 v[66:81], v[138:141], v[248:251], v[66:81]
	v_cvt_pk_bf16_f32 v144, v158, v159
	v_cvt_pk_bf16_f32 v145, v160, v161
	s_nop 0
	v_permlane32_swap_b32_e32 v142, v144
	v_permlane32_swap_b32_e32 v143, v145
	v_mov_b32_e32 v240, v252
	ds_read_b64_tr_b16 v[248:249], v253 offset:0x3200
	ds_read_b64_tr_b16 v[250:251], v253 offset:0x3a00
	s_waitcnt lgkmcnt(10)
	v_mfma_f32_32x32x16_bf16 v[50:65], v[138:141], v[224:227], v[50:65]
	s_nop 1
	v_permlane32_swap_b32_e32 v252, v240
	v_add_f32_e32 v240, v252, v240
	v_fma_f32 v223, v223, v243, v240
	ds_read_b64_tr_b16 v[224:225], v253 offset:0x3400
	ds_read_b64_tr_b16 v[226:227], v253 offset:0x3c00
	s_waitcnt lgkmcnt(10)
	v_mfma_f32_32x32x16_bf16 v[34:49], v[138:141], v[228:231], v[34:49]
	ds_read_b64_tr_b16 v[228:229], v253 offset:0x3600
	ds_read_b64_tr_b16 v[230:231], v253 offset:0x3e00
	s_waitcnt lgkmcnt(10)
	v_mfma_f32_32x32x16_bf16 v[18:33], v[138:141], v[232:235], v[18:33]
	ds_read_b64_tr_b16 v[232:233], v253 offset:0x7000
	ds_read_b64_tr_b16 v[234:235], v253 offset:0x7800
	s_waitcnt lgkmcnt(10)
	v_mfma_f32_32x32x16_bf16 v[2:17], v[138:141], v[236:239], v[2:17]
	ds_read_b64_tr_b16 v[236:237], v253 offset:0x7200
	ds_read_b64_tr_b16 v[238:239], v253 offset:0x7a00
	s_waitcnt lgkmcnt(10)
	v_mfma_f32_32x32x16_bf16 v[114:129], v[142:145], v[244:247], v[114:129]
	ds_read_b64_tr_b16 v[244:245], v253 offset:0x7400
	ds_read_b64_tr_b16 v[246:247], v253 offset:0x7c00
	s_waitcnt lgkmcnt(10)
	v_mfma_f32_32x32x16_bf16 v[98:113], v[142:145], v[248:251], v[98:113]
	ds_read_b64_tr_b16 v[248:249], v253 offset:0x7600
	ds_read_b64_tr_b16 v[250:251], v253 offset:0x7e00
	s_waitcnt lgkmcnt(10)
	v_mfma_f32_32x32x16_bf16 v[82:97], v[142:145], v[224:227], v[82:97]
	s_waitcnt lgkmcnt(8)
	v_mfma_f32_32x32x16_bf16 v[66:81], v[142:145], v[228:231], v[66:81]
	s_waitcnt lgkmcnt(6)
	v_mfma_f32_32x32x16_bf16 v[50:65], v[142:145], v[232:235], v[50:65]
	s_waitcnt lgkmcnt(4)
	v_mfma_f32_32x32x16_bf16 v[34:49], v[142:145], v[236:239], v[34:49]
	s_waitcnt lgkmcnt(2)
	v_mfma_f32_32x32x16_bf16 v[18:33], v[142:145], v[244:247], v[18:33]
	s_waitcnt lgkmcnt(0)
	v_mfma_f32_32x32x16_bf16 v[2:17], v[142:145], v[248:251], v[2:17]
	s_cmp_eq_u32 s23, 64
	s_cbranch_scc0 .LBB0_134
	v_mov_b32_e32 v146, v223
	s_branch .LBB0_143
; __device__ __forceinline__ int crow(int r, int hi) { return (r & 3) + 8 * (r >> 2) + 4 * hi; }
; template <int LDQ, int LDK, int LDV, int LDO>
; __device__ __forceinline__ void attn256_body(const int tid, const bf16_t* __restrict__ Qb, const bf16_t* __restrict__ Kh, const bf16_t* __restrict__ Vh, bf16_t* __restrict__ Ob, int seq, char* lds, LAS unsigned char* ldsl) {
;     ...
;         if (__any(alpha < 1.f)) { if (hi == 0) al_l[r32] = alpha; asm volatile("s_waitcnt lgkmcnt(0)" ::: "memory");
; #pragma unroll
;             for (int r = 0; r < 16; ++r) { const float f = al_l[crow(r, hi)];
; #pragma unroll
;                 for (int d = 0; d < 8; ++d) o[d][r] *= f; } }
.Lattn_rescale:
	s_and_saveexec_b64 s[6:7], s[4:5]
	ds_write_b32 v217, v243 offset:128
	s_or_b64 exec, exec, s[6:7]
	s_waitcnt lgkmcnt(0)
	v_add_u32_e32 v240, s17, v194
	ds_read_b128 v[224:227], v240 offset:128
	ds_read_b128 v[228:231], v240 offset:160
	ds_read_b128 v[232:235], v240 offset:192
	ds_read_b128 v[236:239], v240 offset:224
	s_waitcnt lgkmcnt(0)
	v_pk_mul_f32 v[114:115], v[114:115], v[224:225]
	v_pk_mul_f32 v[116:117], v[116:117], v[226:227]
	v_pk_mul_f32 v[118:119], v[118:119], v[228:229]
	v_pk_mul_f32 v[120:121], v[120:121], v[230:231]
	v_pk_mul_f32 v[122:123], v[122:123], v[232:233]
	v_pk_mul_f32 v[124:125], v[124:125], v[234:235]
	v_pk_mul_f32 v[126:127], v[126:127], v[236:237]
	v_pk_mul_f32 v[128:129], v[128:129], v[238:239]
	v_pk_mul_f32 v[98:99], v[98:99], v[224:225]
	v_pk_mul_f32 v[100:101], v[100:101], v[226:227]
	v_pk_mul_f32 v[102:103], v[102:103], v[228:229]
	v_pk_mul_f32 v[104:105], v[104:105], v[230:231]
	v_pk_mul_f32 v[106:107], v[106:107], v[232:233]
	v_pk_mul_f32 v[108:109], v[108:109], v[234:235]
	v_pk_mul_f32 v[110:111], v[110:111], v[236:237]
	v_pk_mul_f32 v[112:113], v[112:113], v[238:239]
	v_pk_mul_f32 v[82:83], v[82:83], v[224:225]
	v_pk_mul_f32 v[84:85], v[84:85], v[226:227]
	v_pk_mul_f32 v[86:87], v[86:87], v[228:229]
	v_pk_mul_f32 v[88:89], v[88:89], v[230:231]
	v_pk_mul_f32 v[90:91], v[90:91], v[232:233]
	v_pk_mul_f32 v[92:93], v[92:93], v[234:235]
	v_pk_mul_f32 v[94:95], v[94:95], v[236:237]
	v_pk_mul_f32 v[96:97], v[96:97], v[238:239]
	v_pk_mul_f32 v[66:67], v[66:67], v[224:225]
	v_pk_mul_f32 v[68:69], v[68:69], v[226:227]
	v_pk_mul_f32 v[70:71], v[70:71], v[228:229]
	v_pk_mul_f32 v[72:73], v[72:73], v[230:231]
	v_pk_mul_f32 v[74:75], v[74:75], v[232:233]
	v_pk_mul_f32 v[76:77], v[76:77], v[234:235]
	v_pk_mul_f32 v[78:79], v[78:79], v[236:237]
	v_pk_mul_f32 v[80:81], v[80:81], v[238:239]
	v_pk_mul_f32 v[50:51], v[50:51], v[224:225]
	v_pk_mul_f32 v[52:53], v[52:53], v[226:227]
	v_pk_mul_f32 v[54:55], v[54:55], v[228:229]
	v_pk_mul_f32 v[56:57], v[56:57], v[230:231]
	v_pk_mul_f32 v[58:59], v[58:59], v[232:233]
	v_pk_mul_f32 v[60:61], v[60:61], v[234:235]
	v_pk_mul_f32 v[62:63], v[62:63], v[236:237]
	v_pk_mul_f32 v[64:65], v[64:65], v[238:239]
	v_pk_mul_f32 v[34:35], v[34:35], v[224:225]
	v_pk_mul_f32 v[36:37], v[36:37], v[226:227]
	v_pk_mul_f32 v[38:39], v[38:39], v[228:229]
	v_pk_mul_f32 v[40:41], v[40:41], v[230:231]
	v_pk_mul_f32 v[42:43], v[42:43], v[232:233]
	v_pk_mul_f32 v[44:45], v[44:45], v[234:235]
	v_pk_mul_f32 v[46:47], v[46:47], v[236:237]
	v_pk_mul_f32 v[48:49], v[48:49], v[238:239]
	v_pk_mul_f32 v[18:19], v[18:19], v[224:225]
	v_pk_mul_f32 v[20:21], v[20:21], v[226:227]
	v_pk_mul_f32 v[22:23], v[22:23], v[228:229]
	v_pk_mul_f32 v[24:25], v[24:25], v[230:231]
	v_pk_mul_f32 v[26:27], v[26:27], v[232:233]
	v_pk_mul_f32 v[28:29], v[28:29], v[234:235]
	v_pk_mul_f32 v[30:31], v[30:31], v[236:237]
	v_pk_mul_f32 v[32:33], v[32:33], v[238:239]
	v_pk_mul_f32 v[2:3], v[2:3], v[224:225]
	v_pk_mul_f32 v[4:5], v[4:5], v[226:227]
	v_pk_mul_f32 v[6:7], v[6:7], v[228:229]
	v_pk_mul_f32 v[8:9], v[8:9], v[230:231]
	v_pk_mul_f32 v[10:11], v[10:11], v[232:233]
	v_pk_mul_f32 v[12:13], v[12:13], v[234:235]
	v_pk_mul_f32 v[14:15], v[14:15], v[236:237]
	v_pk_mul_f32 v[16:17], v[16:17], v[238:239]
	ds_read_b64_tr_b16 v[244:245], v253 offset:0
	ds_read_b64_tr_b16 v[246:247], v253 offset:0x800
	ds_read_b64_tr_b16 v[248:249], v253 offset:0x200
	ds_read_b64_tr_b16 v[250:251], v253 offset:0xa00
	ds_read_b64_tr_b16 v[224:225], v253 offset:0x400
	ds_read_b64_tr_b16 v[226:227], v253 offset:0xc00
	ds_read_b64_tr_b16 v[228:229], v253 offset:0x600
	ds_read_b64_tr_b16 v[230:231], v253 offset:0xe00
	ds_read_b64_tr_b16 v[232:233], v253 offset:0x4000
	ds_read_b64_tr_b16 v[234:235], v253 offset:0x4800
	ds_read_b64_tr_b16 v[236:237], v253 offset:0x4200
	ds_read_b64_tr_b16 v[238:239], v253 offset:0x4a00
	s_branch .Lattn_resc_done

; __device__ __forceinline__ void convert_tile(const int tid, float* lt, const float* src0, const float* src1, const float* gain, bf16_t* dst, int K, int Nsrc, int mode, int tile) {
;     ...
;     bool sec; const int col = cvt_col(mode, n0 + c4, Nsrc, sec); const float* sp = sec ? src1 : src0;
;     f32x4 v[8];
; #pragma unroll
;     for (int i = 0; i < 8; ++i) { v[i] = (f32x4){0.f, 0.f, 0.f, 0.f}; if (col >= 0) v[i] = *(const f32x4*)(sp + (size_t)(k0 + kr + 8 * i) * Nsrc + col); }
;     if (gain) {
; #pragma unroll
;         for (int i = 0; i < 8; ++i) v[i] *= gain[k0 + kr + 8 * i]; }
.LBB0_149:
	s_andn2_b64 vcc, exec, s[0:1]
	s_cbranch_vccnz .LBB0_153
	s_lshl_b32 s0, s4, 6
	s_and_b32 s1, s0, 0x7c0
	s_lshr_b32 s0, s4, 5
	v_readlane_b32 s4, v255, 4
	v_and_b32_e32 v2, 32, v209
	v_cmp_eq_u32_e32 vcc, 0, v2
	v_mov_b32_e32 v3, s4
	v_readlane_b32 s4, v255, 2
	v_lshlrev_b32_e32 v35, 2, v208
	v_and_b32_e32 v0, 0x7c, v35
	v_mov_b32_e32 v5, s4
	v_readlane_b32 s4, v255, 5
	v_cndmask_b32_e32 v3, v3, v5, vcc
	v_lshl_or_b32 v0, s0, 7, v0
	v_mov_b32_e32 v2, s4
	v_readlane_b32 s4, v255, 3
	v_add_u32_e32 v36, s1, v4
	s_nop 0
	v_mov_b32_e32 v5, s4
	v_cndmask_b32_e32 v2, v2, v5, vcc
	v_lshl_add_u64 v[2:3], v[2:3], 0, s[12:13]
	v_lshl_add_u64 v[2:3], v[0:1], 2, v[2:3]
	v_add_u32_e32 v0, 8, v36
	v_mad_i64_i32 v[4:5], s[4:5], v36, s91, v[2:3]
	v_mad_i64_i32 v[6:7], s[4:5], v0, s91, v[2:3]
	v_add_u32_e32 v0, 16, v36
	global_load_dwordx4 v[30:33], v[4:5], off
	global_load_dwordx4 v[14:17], v[6:7], off
	v_mad_i64_i32 v[4:5], s[4:5], v0, s91, v[2:3]
	v_add_u32_e32 v0, 24, v36
	v_mad_i64_i32 v[6:7], s[4:5], v0, s91, v[2:3]
	v_add_u32_e32 v0, 32, v36
	global_load_dwordx4 v[26:29], v[4:5], off
	global_load_dwordx4 v[10:13], v[6:7], off
	v_mad_i64_i32 v[4:5], s[4:5], v0, s91, v[2:3]
	v_add_u32_e32 v0, 40, v36
	v_mad_i64_i32 v[6:7], s[4:5], v0, s91, v[2:3]
	v_add_u32_e32 v0, 48, v36
	global_load_dwordx4 v[22:25], v[4:5], off
	s_nop 0
	global_load_dwordx4 v[6:9], v[6:7], off
	v_mad_i64_i32 v[4:5], s[4:5], v0, s91, v[2:3]
	v_add_u32_e32 v0, 56, v36
	v_mad_i64_i32 v[2:3], s[4:5], v0, s91, v[2:3]
	global_load_dwordx4 v[18:21], v[4:5], off
	s_nop 0
	global_load_dwordx4 v[2:5], v[2:3], off
	v_readlane_b32 s4, v255, 12
	v_readlane_b32 s5, v255, 13
	s_andn2_b64 vcc, exec, s[4:5]
	s_cbranch_vccnz .LBB0_152
	v_readlane_b32 s4, v255, 15
	v_ashrrev_i32_e32 v37, 31, v36
	v_readlane_b32 s5, v255, 16
	s_nop 1
	v_lshl_add_u64 v[36:37], v[36:37], 2, s[4:5]
	global_load_dword v0, v[36:37], off
	global_load_dword v56, v[36:37], off offset:32
	global_load_dword v58, v[36:37], off offset:64
	global_load_dword v60, v[36:37], off offset:96
	global_load_dword v62, v[36:37], off offset:128
	global_load_dword v64, v[36:37], off offset:160
	global_load_dword v66, v[36:37], off offset:192
	s_nop 0
	global_load_dword v36, v[36:37], off offset:224
	s_waitcnt vmcnt(0)
	v_pk_mul_f32 v[32:33], v[32:33], v[0:1] op_sel_hi:[1,0]
	v_pk_mul_f32 v[30:31], v[30:31], v[0:1] op_sel_hi:[1,0]
	v_pk_mul_f32 v[16:17], v[16:17], v[56:57] op_sel_hi:[1,0]
	v_pk_mul_f32 v[14:15], v[14:15], v[56:57] op_sel_hi:[1,0]
	v_pk_mul_f32 v[28:29], v[28:29], v[58:59] op_sel_hi:[1,0]
	v_pk_mul_f32 v[26:27], v[26:27], v[58:59] op_sel_hi:[1,0]
	v_pk_mul_f32 v[12:13], v[12:13], v[60:61] op_sel_hi:[1,0]
	v_pk_mul_f32 v[10:11], v[10:11], v[60:61] op_sel_hi:[1,0]
	v_pk_mul_f32 v[24:25], v[24:25], v[62:63] op_sel_hi:[1,0]
	v_pk_mul_f32 v[22:23], v[22:23], v[62:63] op_sel_hi:[1,0]
	v_pk_mul_f32 v[8:9], v[8:9], v[64:65] op_sel_hi:[1,0]
	v_pk_mul_f32 v[6:7], v[6:7], v[64:65] op_sel_hi:[1,0]
	v_pk_mul_f32 v[20:21], v[20:21], v[66:67] op_sel_hi:[1,0]
	v_pk_mul_f32 v[18:19], v[18:19], v[66:67] op_sel_hi:[1,0]
	v_pk_mul_f32 v[4:5], v[4:5], v[36:37] op_sel_hi:[1,0]
	v_pk_mul_f32 v[2:3], v[2:3], v[36:37] op_sel_hi:[1,0]

; #define PG8_STAGE(bufoff, gbase, voff) do { _Pragma("unroll") for (int _i = 0; _i < 2; ++_i) \
;         __builtin_amdgcn_global_load_lds((const unsigned*)((const char*)(gbase) + (voff)[_i]), (LAS unsigned*)(lds + (bufoff) + ldsw + _i * 8192), 16, 0, 0); } while (0)
; #define PG8_LDA(dst, b, h) do { _Pragma("unroll") for (int m = 0; m < 4; ++m) _Pragma("unroll") for (int k = 0; k < 2; ++k) dst[m][k] = *(const LAS bf16x8*)(lds + PG8_SA(b, h) + aoff + m * 2048 + k * 1024); } while (0)
; #define PG8_LDB(dst, b, h) do { _Pragma("unroll") for (int n = 0; n < 2; ++n) _Pragma("unroll") for (int k = 0; k < 2; ++k) dst[n][k] = *(const LAS bf16x8*)(lds + PG8_SB(b, h) + boff + n * 2048 + k * 1024); } while (0)
; #define PG8_WAIT_V(n) asm volatile("s_waitcnt vmcnt(" #n ")" ::: "memory")
; #define PG8_WAIT_L(n) asm volatile("s_waitcnt lgkmcnt(" #n ")" ::: "memory")
; #define PG8_BAR __builtin_amdgcn_s_barrier()
; #define PG8_SCHED __builtin_amdgcn_sched_barrier(0)
; template <class Epi>
; __device__ __forceinline__ void gemm_phase(const int tid, LAS unsigned char* lds, const Gemm g, const StaticOrder& S, const Epi& E) {
;     ...
;             PG8_LDB(B0, 0, 0); PG8_SCHED; PG8_LDA(At, 0, 0);
;             PG8_WAIT_L(8); PG8_BAR; PG8_WAIT_L(0); PG8_MMA(0, 0, At, B0); PG8_BAR; PG8_SCHED;
;             PG8_LDB(B1, 0, 1); PG8_STAGE(PG8_SB(0, 0), b2, voffB);
;             PG8_BAR; PG8_WAIT_L(0); PG8_MMA(0, 1, At, B1); PG8_BAR;
;             PG8_LDA(At, 0, 1); PG8_STAGE(PG8_SA(0, 0), a2, voffA);
;             PG8_BAR; PG8_WAIT_L(0); PG8_MMA(1, 0, At, B0); PG8_BAR; PG8_SCHED;
;             PG8_STAGE(PG8_SB(0, 1), b2 + hstep, voffB);
;             { const int first_ = __builtin_amdgcn_readfirstlane((ui > 0 && t == 0) ? 1 : 0);
;               if constexpr (Epi::SMIN == 8) asm volatile("s_cmp_eq_u32 %0, 0\n\ts_cbranch_scc1 .Lws_a%=\n\ts_waitcnt vmcnt(14)\n\ts_branch .Lws_b%=\n.Lws_a%=:\n\ts_waitcnt vmcnt(6)\n.Lws_b%=:" :: "s"(first_) : "memory", "scc");
;               else if constexpr (Epi::SMIN == 24) asm volatile("s_cmp_eq_u32 %0, 0\n\ts_cbranch_scc1 .Lws_a%=\n\ts_waitcnt vmcnt(30)\n\ts_branch .Lws_b%=\n.Lws_a%=:\n\ts_waitcnt vmcnt(6)\n.Lws_b%=:" :: "s"(first_) : "memory", "scc");
;               else PG8_WAIT_V(6); }
;             PG8_BAR; PG8_MMA(1, 1, At, B1); PG8_BAR;
.LBB0_336:
	s_add_i32 s51, 0, 0x10000
	v_add_u32_e32 v0, s51, v221
	ds_read_b128 v[130:133], v0
	ds_read_b128 v[134:137], v0 offset:1024
	ds_read_b128 v[138:141], v0 offset:2048
	ds_read_b128 v[142:145], v0 offset:3072
	s_cmp_eq_u32 s50, 28
	s_cselect_b32 s1, s24, s39
	s_cselect_b32 s0, s25, s28
	s_cselect_b32 s11, s23, s49
	s_cselect_b32 s10, s27, s48
	ds_read_b128 v[146:149], v225
	ds_read_b128 v[150:153], v225 offset:1024
	ds_read_b128 v[154:157], v225 offset:2048
	ds_read_b128 v[158:161], v225 offset:3072
	ds_read_b128 v[162:165], v225 offset:4096
	ds_read_b128 v[166:169], v225 offset:5120
	ds_read_b128 v[170:173], v225 offset:6144
	ds_read_b128 v[174:177], v225 offset:7168
	s_waitcnt lgkmcnt(8)
	s_barrier
	s_setprio 1
	s_waitcnt lgkmcnt(7)
	v_mfma_f32_16x16x32_bf16 v[126:129], v[130:133], v[146:149], v[126:129]
	v_mfma_f32_16x16x32_bf16 v[122:125], v[138:141], v[146:149], v[122:125]
	s_waitcnt lgkmcnt(5)
	v_mfma_f32_16x16x32_bf16 v[110:113], v[130:133], v[154:157], v[110:113]
	v_mfma_f32_16x16x32_bf16 v[106:109], v[138:141], v[154:157], v[106:109]
	s_waitcnt lgkmcnt(3)
	v_mfma_f32_16x16x32_bf16 v[94:97], v[130:133], v[162:165], v[94:97]
	v_mfma_f32_16x16x32_bf16 v[90:93], v[138:141], v[162:165], v[90:93]
	s_waitcnt lgkmcnt(1)
	v_mfma_f32_16x16x32_bf16 v[78:81], v[130:133], v[170:173], v[78:81]
	v_mfma_f32_16x16x32_bf16 v[74:77], v[138:141], v[170:173], v[74:77]
	v_mfma_f32_16x16x32_bf16 v[126:129], v[134:137], v[150:153], v[126:129]
	v_mfma_f32_16x16x32_bf16 v[122:125], v[142:145], v[150:153], v[122:125]
	v_mfma_f32_16x16x32_bf16 v[110:113], v[134:137], v[158:161], v[110:113]
	v_mfma_f32_16x16x32_bf16 v[106:109], v[142:145], v[158:161], v[106:109]
	v_mfma_f32_16x16x32_bf16 v[94:97], v[134:137], v[166:169], v[94:97]
	v_mfma_f32_16x16x32_bf16 v[90:93], v[142:145], v[166:169], v[90:93]
	s_waitcnt lgkmcnt(0)
	v_mfma_f32_16x16x32_bf16 v[78:81], v[134:137], v[174:177], v[78:81]
	v_mfma_f32_16x16x32_bf16 v[74:77], v[142:145], v[174:177], v[74:77]
	s_setprio 0
	s_barrier
	s_add_i32 s54, 0, 0x14000
	s_add_i32 s51, s51, s37
	v_add_u32_e32 v0, s54, v221
	v_lshl_add_u64 v[212:213], s[10:11], 0, v[198:199]
	s_mov_b32 m0, s51
	ds_read_b128 v[178:181], v0
	ds_read_b128 v[182:185], v0 offset:1024
	ds_read_b128 v[186:189], v0 offset:2048
	ds_read_b128 v[190:193], v0 offset:3072
	global_load_lds_dwordx4 v[212:213], off
	v_lshl_add_u64 v[214:215], s[10:11], 0, v[194:195]
	s_add_i32 m0, s51, 0x2000
	s_nop 0
	global_load_lds_dwordx4 v[214:215], off
	s_barrier
	s_setprio 1
	s_waitcnt lgkmcnt(3)
	v_mfma_f32_16x16x32_bf16 v[118:121], v[178:181], v[146:149], v[118:121]
	s_waitcnt lgkmcnt(1)
	v_mfma_f32_16x16x32_bf16 v[114:117], v[186:189], v[146:149], v[114:117]
	v_mfma_f32_16x16x32_bf16 v[102:105], v[178:181], v[154:157], v[102:105]
	v_mfma_f32_16x16x32_bf16 v[98:101], v[186:189], v[154:157], v[98:101]
	v_mfma_f32_16x16x32_bf16 v[86:89], v[178:181], v[162:165], v[86:89]
	v_mfma_f32_16x16x32_bf16 v[82:85], v[186:189], v[162:165], v[82:85]
	v_mfma_f32_16x16x32_bf16 v[70:73], v[178:181], v[170:173], v[70:73]
	v_mfma_f32_16x16x32_bf16 v[66:69], v[186:189], v[170:173], v[66:69]
	v_mfma_f32_16x16x32_bf16 v[118:121], v[182:185], v[150:153], v[118:121]
	s_waitcnt lgkmcnt(0)
	v_mfma_f32_16x16x32_bf16 v[114:117], v[190:193], v[150:153], v[114:117]
	v_mfma_f32_16x16x32_bf16 v[102:105], v[182:185], v[158:161], v[102:105]
	v_mfma_f32_16x16x32_bf16 v[98:101], v[190:193], v[158:161], v[98:101]
	v_mfma_f32_16x16x32_bf16 v[86:89], v[182:185], v[166:169], v[86:89]
	v_mfma_f32_16x16x32_bf16 v[82:85], v[190:193], v[166:169], v[82:85]
	v_mfma_f32_16x16x32_bf16 v[70:73], v[182:185], v[174:177], v[70:73]
	v_mfma_f32_16x16x32_bf16 v[66:69], v[190:193], v[174:177], v[66:69]
	s_setprio 0
	s_mov_b32 m0, s46
	v_lshl_add_u64 v[216:217], s[0:1], 0, v[200:201]
	s_barrier
	ds_read_b128 v[146:149], v225 offset:16384
	ds_read_b128 v[150:153], v225 offset:17408
	ds_read_b128 v[154:157], v225 offset:18432
	ds_read_b128 v[158:161], v225 offset:19456
	ds_read_b128 v[162:165], v225 offset:20480
	ds_read_b128 v[166:169], v225 offset:21504
	ds_read_b128 v[170:173], v225 offset:22528
	ds_read_b128 v[174:177], v225 offset:23552
	global_load_lds_dwordx4 v[216:217], off
	v_lshl_add_u64 v[218:219], s[0:1], 0, v[196:197]
	s_mov_b32 m0, s47
	s_nop 0
	global_load_lds_dwordx4 v[218:219], off
	s_barrier
	s_setprio 1
	s_waitcnt lgkmcnt(7)
	v_mfma_f32_16x16x32_bf16 v[62:65], v[130:133], v[146:149], v[62:65]
	v_mfma_f32_16x16x32_bf16 v[58:61], v[138:141], v[146:149], v[58:61]
	s_waitcnt lgkmcnt(5)
	v_mfma_f32_16x16x32_bf16 v[46:49], v[130:133], v[154:157], v[46:49]
	v_mfma_f32_16x16x32_bf16 v[42:45], v[138:141], v[154:157], v[42:45]
	s_waitcnt lgkmcnt(3)
	v_mfma_f32_16x16x32_bf16 v[30:33], v[130:133], v[162:165], v[30:33]
	v_mfma_f32_16x16x32_bf16 v[26:29], v[138:141], v[162:165], v[26:29]
	s_waitcnt lgkmcnt(1)
	v_mfma_f32_16x16x32_bf16 v[14:17], v[130:133], v[170:173], v[14:17]
	v_mfma_f32_16x16x32_bf16 v[10:13], v[138:141], v[170:173], v[10:13]
	v_mfma_f32_16x16x32_bf16 v[62:65], v[134:137], v[150:153], v[62:65]
	v_mfma_f32_16x16x32_bf16 v[58:61], v[142:145], v[150:153], v[58:61]
	v_mfma_f32_16x16x32_bf16 v[46:49], v[134:137], v[158:161], v[46:49]
	v_mfma_f32_16x16x32_bf16 v[42:45], v[142:145], v[158:161], v[42:45]
	v_mfma_f32_16x16x32_bf16 v[30:33], v[134:137], v[166:169], v[30:33]
	v_mfma_f32_16x16x32_bf16 v[26:29], v[142:145], v[166:169], v[26:29]
	s_waitcnt lgkmcnt(0)
	v_mfma_f32_16x16x32_bf16 v[14:17], v[134:137], v[174:177], v[14:17]
	v_mfma_f32_16x16x32_bf16 v[10:13], v[142:145], v[174:177], v[10:13]
	s_setprio 0
	s_barrier
; #define PG8_STAGE(bufoff, gbase, voff) do { _Pragma("unroll") for (int _i = 0; _i < 2; ++_i) \
;         __builtin_amdgcn_global_load_lds((const unsigned*)((const char*)(gbase) + (voff)[_i]), (LAS unsigned*)(lds + (bufoff) + ldsw + _i * 8192), 16, 0, 0); } while (0)
; #define PG8_LDA(dst, b, h) do { _Pragma("unroll") for (int m = 0; m < 4; ++m) _Pragma("unroll") for (int k = 0; k < 2; ++k) dst[m][k] = *(const LAS bf16x8*)(lds + PG8_SA(b, h) + aoff + m * 2048 + k * 1024); } while (0)
; #define PG8_LDB(dst, b, h) do { _Pragma("unroll") for (int n = 0; n < 2; ++n) _Pragma("unroll") for (int k = 0; k < 2; ++k) dst[n][k] = *(const LAS bf16x8*)(lds + PG8_SB(b, h) + boff + n * 2048 + k * 1024); } while (0)
; #define PG8_MMA(ai, bj, At, Bt) do { __builtin_amdgcn_s_setprio(1); _Pragma("unroll") for (int m = 0; m < 4; ++m) _Pragma("unroll") for (int n = 0; n < 2; ++n) _Pragma("unroll") for (int k = 0; k < 2; ++k) \
;         acc[ai][bj][m][n] = __builtin_amdgcn_mfma_f32_16x16x32_bf16(Bt[n][k], At[m][k], acc[ai][bj][m][n], 0, 0, 0); __builtin_amdgcn_s_setprio(0); } while (0)
; #define PG8_WAIT_L(n) asm volatile("s_waitcnt lgkmcnt(" #n ")" ::: "memory")
; #define PG8_BAR __builtin_amdgcn_s_barrier()
; #define PG8_SCHED __builtin_amdgcn_sched_barrier(0)
; template <class Epi>
; __device__ __forceinline__ void gemm_phase(const int tid, LAS unsigned char* lds, const Gemm g, const StaticOrder& S, const Epi& E) {
;     ...
;             PG8_BAR; PG8_MMA(1, 1, At, B1); PG8_BAR;
;             PG8_LDB(B0, 1, 0); PG8_SCHED; PG8_LDA(At, 1, 0); PG8_STAGE(PG8_SA(0, 1), a2 + hstep, voffA);
;             PG8_WAIT_L(8); PG8_BAR; PG8_WAIT_L(0); PG8_MMA(0, 0, At, B0); PG8_BAR; PG8_SCHED;
;             PG8_LDB(B1, 1, 1); PG8_STAGE(PG8_SB(1, 0), b3, voffB);
;             PG8_BAR; PG8_WAIT_L(0); PG8_MMA(0, 1, At, B1); PG8_BAR;
;             PG8_LDA(At, 1, 1); PG8_STAGE(PG8_SA(1, 0), a3, voffA);
;             PG8_BAR; PG8_WAIT_L(0); PG8_MMA(1, 0, At, B0); PG8_BAR; PG8_SCHED;
	s_add_u32 s66, s10, 0x80000
	s_addc_u32 s67, s11, 0
	s_add_i32 s51, s54, s37
	v_lshl_add_u64 v[130:131], s[66:67], 0, v[198:199]
	s_mov_b32 m0, s51
	s_nop 0
	global_load_lds_dwordx4 v[130:131], off
	v_lshl_add_u64 v[130:131], s[66:67], 0, v[194:195]
	s_add_i32 m0, s51, 0x2000
	s_nop 0
	global_load_lds_dwordx4 v[130:131], off
	s_waitcnt vmcnt(6)
	s_barrier
	s_setprio 1
	v_mfma_f32_16x16x32_bf16 v[54:57], v[178:181], v[146:149], v[54:57]
	v_mfma_f32_16x16x32_bf16 v[50:53], v[186:189], v[146:149], v[50:53]
	v_mfma_f32_16x16x32_bf16 v[38:41], v[178:181], v[154:157], v[38:41]
	v_mfma_f32_16x16x32_bf16 v[34:37], v[186:189], v[154:157], v[34:37]
	v_mfma_f32_16x16x32_bf16 v[22:25], v[178:181], v[162:165], v[22:25]
	v_mfma_f32_16x16x32_bf16 v[18:21], v[186:189], v[162:165], v[18:21]
	v_mfma_f32_16x16x32_bf16 v[6:9], v[178:181], v[170:173], v[6:9]
	v_mfma_f32_16x16x32_bf16 v[2:5], v[186:189], v[170:173], v[2:5]
	v_mfma_f32_16x16x32_bf16 v[54:57], v[182:185], v[150:153], v[54:57]
	v_mfma_f32_16x16x32_bf16 v[50:53], v[190:193], v[150:153], v[50:53]
	v_mfma_f32_16x16x32_bf16 v[38:41], v[182:185], v[158:161], v[38:41]
	v_mfma_f32_16x16x32_bf16 v[34:37], v[190:193], v[158:161], v[34:37]
	v_mfma_f32_16x16x32_bf16 v[22:25], v[182:185], v[166:169], v[22:25]
	v_mfma_f32_16x16x32_bf16 v[18:21], v[190:193], v[166:169], v[18:21]
	v_mfma_f32_16x16x32_bf16 v[6:9], v[182:185], v[174:177], v[6:9]
	v_mfma_f32_16x16x32_bf16 v[2:5], v[190:193], v[174:177], v[2:5]
	s_setprio 0
	s_add_i32 s51, 0, 0x18000
	v_add_u32_e32 v0, s51, v221
	s_barrier
	ds_read_b128 v[130:133], v0
	ds_read_b128 v[134:137], v0 offset:1024
	ds_read_b128 v[138:141], v0 offset:2048
	ds_read_b128 v[142:145], v0 offset:3072
	s_add_u32 s66, s0, 0x80000
	s_addc_u32 s67, s1, 0
	s_mov_b32 m0, s58
	v_lshl_add_u64 v[178:179], s[66:67], 0, v[200:201]
	ds_read_b128 v[146:149], v225 offset:32768
	ds_read_b128 v[150:153], v225 offset:33792
	ds_read_b128 v[154:157], v225 offset:34816
	ds_read_b128 v[158:161], v225 offset:35840
	ds_read_b128 v[162:165], v225 offset:36864
	ds_read_b128 v[166:169], v225 offset:37888
	ds_read_b128 v[170:173], v225 offset:38912
	ds_read_b128 v[174:177], v225 offset:39936
	global_load_lds_dwordx4 v[178:179], off
	v_lshl_add_u64 v[178:179], s[66:67], 0, v[196:197]
	s_mov_b32 m0, s59
	s_nop 0
	global_load_lds_dwordx4 v[178:179], off
	s_waitcnt lgkmcnt(8)
	s_barrier
	s_setprio 1
	s_waitcnt lgkmcnt(7)
	v_mfma_f32_16x16x32_bf16 v[126:129], v[130:133], v[146:149], v[126:129]
	v_mfma_f32_16x16x32_bf16 v[122:125], v[138:141], v[146:149], v[122:125]
	s_waitcnt lgkmcnt(5)
	v_mfma_f32_16x16x32_bf16 v[110:113], v[130:133], v[154:157], v[110:113]
	v_mfma_f32_16x16x32_bf16 v[106:109], v[138:141], v[154:157], v[106:109]
	s_waitcnt lgkmcnt(3)
	v_mfma_f32_16x16x32_bf16 v[94:97], v[130:133], v[162:165], v[94:97]
	v_mfma_f32_16x16x32_bf16 v[90:93], v[138:141], v[162:165], v[90:93]
	s_waitcnt lgkmcnt(1)
	v_mfma_f32_16x16x32_bf16 v[78:81], v[130:133], v[170:173], v[78:81]
	v_mfma_f32_16x16x32_bf16 v[74:77], v[138:141], v[170:173], v[74:77]
	v_mfma_f32_16x16x32_bf16 v[126:129], v[134:137], v[150:153], v[126:129]
	v_mfma_f32_16x16x32_bf16 v[122:125], v[142:145], v[150:153], v[122:125]
	v_mfma_f32_16x16x32_bf16 v[110:113], v[134:137], v[158:161], v[110:113]
	v_mfma_f32_16x16x32_bf16 v[106:109], v[142:145], v[158:161], v[106:109]
	v_mfma_f32_16x16x32_bf16 v[94:97], v[134:137], v[166:169], v[94:97]
	v_mfma_f32_16x16x32_bf16 v[90:93], v[142:145], v[166:169], v[90:93]
	s_waitcnt lgkmcnt(0)
	v_mfma_f32_16x16x32_bf16 v[78:81], v[134:137], v[174:177], v[78:81]
	v_mfma_f32_16x16x32_bf16 v[74:77], v[142:145], v[174:177], v[74:77]
	s_setprio 0
	s_barrier
	s_add_i32 s54, 0, 0x1c000
	s_add_i32 s51, s51, s37
	v_add_u32_e32 v0, s54, v221
	v_lshl_add_u64 v[212:213], v[212:213], 0, s[86:87]
	s_mov_b32 m0, s51
	ds_read_b128 v[178:181], v0
	ds_read_b128 v[182:185], v0 offset:1024
	ds_read_b128 v[186:189], v0 offset:2048
	ds_read_b128 v[190:193], v0 offset:3072
	global_load_lds_dwordx4 v[212:213], off
	v_lshl_add_u64 v[212:213], v[214:215], 0, s[86:87]
	s_add_i32 m0, s51, 0x2000
	s_nop 0
	global_load_lds_dwordx4 v[212:213], off
	s_barrier
	s_setprio 1
	s_waitcnt lgkmcnt(3)
	v_mfma_f32_16x16x32_bf16 v[118:121], v[178:181], v[146:149], v[118:121]
	s_waitcnt lgkmcnt(1)
	v_mfma_f32_16x16x32_bf16 v[114:117], v[186:189], v[146:149], v[114:117]
	v_mfma_f32_16x16x32_bf16 v[102:105], v[178:181], v[154:157], v[102:105]
	v_mfma_f32_16x16x32_bf16 v[98:101], v[186:189], v[154:157], v[98:101]
	v_mfma_f32_16x16x32_bf16 v[86:89], v[178:181], v[162:165], v[86:89]
	v_mfma_f32_16x16x32_bf16 v[82:85], v[186:189], v[162:165], v[82:85]
	v_mfma_f32_16x16x32_bf16 v[70:73], v[178:181], v[170:173], v[70:73]
	v_mfma_f32_16x16x32_bf16 v[66:69], v[186:189], v[170:173], v[66:69]
	v_mfma_f32_16x16x32_bf16 v[118:121], v[182:185], v[150:153], v[118:121]
	s_waitcnt lgkmcnt(0)
	v_mfma_f32_16x16x32_bf16 v[114:117], v[190:193], v[150:153], v[114:117]
	v_mfma_f32_16x16x32_bf16 v[102:105], v[182:185], v[158:161], v[102:105]
	v_mfma_f32_16x16x32_bf16 v[98:101], v[190:193], v[158:161], v[98:101]
	v_mfma_f32_16x16x32_bf16 v[86:89], v[182:185], v[166:169], v[86:89]
	v_mfma_f32_16x16x32_bf16 v[82:85], v[190:193], v[166:169], v[82:85]
	v_mfma_f32_16x16x32_bf16 v[70:73], v[182:185], v[174:177], v[70:73]
	v_mfma_f32_16x16x32_bf16 v[66:69], v[190:193], v[174:177], v[66:69]
	s_setprio 0
	s_mov_b32 m0, s68
	v_lshl_add_u64 v[212:213], v[216:217], 0, s[86:87]
	s_barrier
; #define PG8_STAGE(bufoff, gbase, voff) do { _Pragma("unroll") for (int _i = 0; _i < 2; ++_i) \
;         __builtin_amdgcn_global_load_lds((const unsigned*)((const char*)(gbase) + (voff)[_i]), (LAS unsigned*)(lds + (bufoff) + ldsw + _i * 8192), 16, 0, 0); } while (0)
; #define PG8_LDA(dst, b, h) do { _Pragma("unroll") for (int m = 0; m < 4; ++m) _Pragma("unroll") for (int k = 0; k < 2; ++k) dst[m][k] = *(const LAS bf16x8*)(lds + PG8_SA(b, h) + aoff + m * 2048 + k * 1024); } while (0)
; #define PG8_MMA(ai, bj, At, Bt) do { __builtin_amdgcn_s_setprio(1); _Pragma("unroll") for (int m = 0; m < 4; ++m) _Pragma("unroll") for (int n = 0; n < 2; ++n) _Pragma("unroll") for (int k = 0; k < 2; ++k) \
;         acc[ai][bj][m][n] = __builtin_amdgcn_mfma_f32_16x16x32_bf16(Bt[n][k], At[m][k], acc[ai][bj][m][n], 0, 0, 0); __builtin_amdgcn_s_setprio(0); } while (0)
; #define PG8_WAIT_V(n) asm volatile("s_waitcnt vmcnt(" #n ")" ::: "memory")
; #define PG8_WAIT_L(n) asm volatile("s_waitcnt lgkmcnt(" #n ")" ::: "memory")
; #define PG8_BAR __builtin_amdgcn_s_barrier()
; #define PG8_SCHED __builtin_amdgcn_sched_barrier(0)
; template <class Epi>
; __device__ __forceinline__ void gemm_phase(const int tid, LAS unsigned char* lds, const Gemm g, const StaticOrder& S, const Epi& E) {
;     ...
;             PG8_LDA(At, 1, 1); PG8_STAGE(PG8_SA(1, 0), a3, voffA);
;             PG8_BAR; PG8_WAIT_L(0); PG8_MMA(1, 0, At, B0); PG8_BAR; PG8_SCHED;
;             PG8_STAGE(PG8_SB(1, 1), b3 + hstep, voffB);
;             PG8_WAIT_V(6); PG8_BAR; PG8_STAGE(PG8_SA(1, 1), a3 + hstep, voffA);
;             PG8_MMA(1, 1, At, B1); PG8_BAR;
;         }
;         E(acc, cur, wr, wc, fr, fq, rsc);
	ds_read_b128 v[146:149], v225 offset:49152
	ds_read_b128 v[150:153], v225 offset:50176
	ds_read_b128 v[154:157], v225 offset:51200
	ds_read_b128 v[158:161], v225 offset:52224
	ds_read_b128 v[162:165], v225 offset:53248
	ds_read_b128 v[166:169], v225 offset:54272
	ds_read_b128 v[170:173], v225 offset:55296
	ds_read_b128 v[174:177], v225 offset:56320
	global_load_lds_dwordx4 v[212:213], off
	v_lshl_add_u64 v[212:213], v[218:219], 0, s[86:87]
	s_mov_b32 m0, s69
	s_nop 0
	global_load_lds_dwordx4 v[212:213], off
	s_barrier
	s_setprio 1
	s_waitcnt lgkmcnt(7)
	v_mfma_f32_16x16x32_bf16 v[62:65], v[130:133], v[146:149], v[62:65]
	v_mfma_f32_16x16x32_bf16 v[58:61], v[138:141], v[146:149], v[58:61]
	s_waitcnt lgkmcnt(5)
	v_mfma_f32_16x16x32_bf16 v[46:49], v[130:133], v[154:157], v[46:49]
	v_mfma_f32_16x16x32_bf16 v[42:45], v[138:141], v[154:157], v[42:45]
	s_waitcnt lgkmcnt(3)
	v_mfma_f32_16x16x32_bf16 v[30:33], v[130:133], v[162:165], v[30:33]
	v_mfma_f32_16x16x32_bf16 v[26:29], v[138:141], v[162:165], v[26:29]
	s_waitcnt lgkmcnt(1)
	v_mfma_f32_16x16x32_bf16 v[14:17], v[130:133], v[170:173], v[14:17]
	v_mfma_f32_16x16x32_bf16 v[10:13], v[138:141], v[170:173], v[10:13]
	v_mfma_f32_16x16x32_bf16 v[62:65], v[134:137], v[150:153], v[62:65]
	v_mfma_f32_16x16x32_bf16 v[58:61], v[142:145], v[150:153], v[58:61]
	v_mfma_f32_16x16x32_bf16 v[46:49], v[134:137], v[158:161], v[46:49]
	v_mfma_f32_16x16x32_bf16 v[42:45], v[142:145], v[158:161], v[42:45]
	v_mfma_f32_16x16x32_bf16 v[30:33], v[134:137], v[166:169], v[30:33]
	v_mfma_f32_16x16x32_bf16 v[26:29], v[142:145], v[166:169], v[26:29]
	s_waitcnt lgkmcnt(0)
	v_mfma_f32_16x16x32_bf16 v[14:17], v[134:137], v[174:177], v[14:17]
	v_mfma_f32_16x16x32_bf16 v[10:13], v[142:145], v[174:177], v[10:13]
	s_setprio 0
	s_barrier
	s_add_u32 s10, s10, 0x80080
	s_addc_u32 s11, s11, 0
	s_add_i32 s51, s54, s37
	v_lshl_add_u64 v[130:131], s[10:11], 0, v[198:199]
	s_mov_b32 m0, s51
	s_nop 0
	global_load_lds_dwordx4 v[130:131], off
	s_add_i32 m0, s51, 0x2000
	s_add_u32 s0, s0, 0x80080
	v_lshl_add_u64 v[130:131], s[10:11], 0, v[194:195]
	s_addc_u32 s1, s1, 0
	global_load_lds_dwordx4 v[130:131], off
	v_lshl_add_u64 v[130:131], s[0:1], 0, v[200:201]
	s_mov_b32 m0, s84
	s_waitcnt vmcnt(6)
	s_barrier
	global_load_lds_dwordx4 v[130:131], off
	v_lshl_add_u64 v[130:131], s[0:1], 0, v[196:197]
	s_mov_b32 m0, s85
	s_nop 0
	global_load_lds_dwordx4 v[130:131], off
	s_setprio 1
	v_mfma_f32_16x16x32_bf16 v[54:57], v[178:181], v[146:149], v[54:57]
	v_mfma_f32_16x16x32_bf16 v[50:53], v[186:189], v[146:149], v[50:53]
	v_mfma_f32_16x16x32_bf16 v[38:41], v[178:181], v[154:157], v[38:41]
	v_mfma_f32_16x16x32_bf16 v[34:37], v[186:189], v[154:157], v[34:37]
	v_mfma_f32_16x16x32_bf16 v[22:25], v[178:181], v[162:165], v[22:25]
	v_mfma_f32_16x16x32_bf16 v[18:21], v[186:189], v[162:165], v[18:21]
	v_mfma_f32_16x16x32_bf16 v[6:9], v[178:181], v[170:173], v[6:9]
	v_mfma_f32_16x16x32_bf16 v[2:5], v[186:189], v[170:173], v[2:5]
	v_mfma_f32_16x16x32_bf16 v[54:57], v[182:185], v[150:153], v[54:57]
	v_mfma_f32_16x16x32_bf16 v[50:53], v[190:193], v[150:153], v[50:53]
	v_mfma_f32_16x16x32_bf16 v[38:41], v[182:185], v[158:161], v[38:41]
	v_mfma_f32_16x16x32_bf16 v[34:37], v[190:193], v[158:161], v[34:37]
	v_mfma_f32_16x16x32_bf16 v[22:25], v[182:185], v[166:169], v[22:25]
	v_mfma_f32_16x16x32_bf16 v[18:21], v[190:193], v[166:169], v[18:21]
	v_mfma_f32_16x16x32_bf16 v[6:9], v[182:185], v[174:177], v[6:9]
	v_mfma_f32_16x16x32_bf16 v[2:5], v[190:193], v[174:177], v[2:5]
	s_setprio 0
	s_add_i32 s50, s50, 2
	s_add_u32 s28, s28, 0x100
	s_addc_u32 s39, s39, 0
	s_add_u32 s48, s48, 0x100
	s_addc_u32 s49, s49, 0
	s_cmp_gt_u32 s50, 29
	s_barrier
	s_cbranch_scc0 .LBB0_336
	v_lshl_add_u32 v212, s95, 8, v220
	s_cmp_eq_u32 s26, s95
	v_or_b32_e32 v218, 16, v212
	v_or_b32_e32 v216, 32, v212
	v_or_b32_e32 v214, 48, v212
	s_cbranch_scc1 .LBB0_341
; __device__ __forceinline__ void rows_rstd4(const float* ssqp, int rbase, int fq, float (&rs)[4]) {
;     f32x4 pa_[4], pb_[4];
; #pragma unroll
;     for (int m = 0; m < 4; ++m) { const float* q = ssqp + (size_t)(rbase + m * 16) * 32 + 8 * fq; pa_[m] = *(const f32x4*)q; pb_[m] = *(const f32x4*)(q + 4); }
;     asm volatile("" ::: "memory");
; #pragma unroll
;     for (int m = 0; m < 4; ++m) { const f32x4 a = pa_[m], b = pb_[m];
;         float t = ((a[0] + a[1]) + (a[2] + a[3])) + ((b[0] + b[1]) + (b[2] + b[3]));
;         t = xadd<16>(t); t = xadd<32>(t);
;         rs[m] = __builtin_amdgcn_rsqf(t * (1.0f / DM) + EPS); }
; }
;     __device__ __forceinline__ void operator()(const AccT& acc, const pg8::Unit& u, int wr, int wc, int fr, int fq, pg8::RsCache& rsc) const {
;     ...
;         if (rsc.pm != u.pm) {
;             float r0[4], r1[4]; rows_rstd4(ssq, row0, fq, r0); rows_rstd4(ssq, row0 + 128, fq, r1);
;             if (fq == 0) {
; #pragma unroll
;                 for (int m = 0; m < 4; ++m) { rsc.rl[m * 16 + fr] = r0[m]; rsc.rl[64 + m * 16 + fr] = r1[m]; } }
;             rsc.pm = u.pm; asm volatile("s_waitcnt lgkmcnt(0)" ::: "memory"); }
	v_ashrrev_i32_e32 v213, 31, v212
	v_lshlrev_b64 v[130:131], 7, v[212:213]
	v_lshl_add_u64 v[130:131], v[204:205], 0, v[130:131]
	global_load_dwordx4 v[132:135], v[130:131], off offset:16
	global_load_dwordx4 v[136:139], v[130:131], off
	v_ashrrev_i32_e32 v219, 31, v218
	v_lshlrev_b64 v[140:141], 7, v[218:219]
	v_lshl_add_u64 v[144:145], v[204:205], 0, v[140:141]
	global_load_dwordx4 v[140:143], v[144:145], off offset:16
	s_nop 0
	global_load_dwordx4 v[144:147], v[144:145], off
	v_ashrrev_i32_e32 v217, 31, v216
	v_lshlrev_b64 v[148:149], 7, v[216:217]
	v_lshl_add_u64 v[152:153], v[204:205], 0, v[148:149]
	global_load_dwordx4 v[148:151], v[152:153], off offset:16
	s_nop 0
	global_load_dwordx4 v[152:155], v[152:153], off
	v_ashrrev_i32_e32 v215, 31, v214
	v_lshlrev_b64 v[156:157], 7, v[214:215]
	v_lshl_add_u64 v[160:161], v[204:205], 0, v[156:157]
	global_load_dwordx4 v[156:159], v[160:161], off offset:16
	s_nop 0
	global_load_dwordx4 v[160:163], v[160:161], off
	s_mov_b64 s[0:1], 0x4000
	s_waitcnt vmcnt(0)
	v_add_f32_e32 v132, v132, v133
	v_add_f32_e32 v0, v136, v137
	v_add_f32_e32 v136, v138, v139
	v_add_f32_e32 v133, v134, v135
	v_add_f32_e32 v0, v0, v136
	v_add_f32_e32 v132, v132, v133
	v_add_f32_e32 v0, v0, v132
	ds_swizzle_b32 v132, v0 offset:swizzle(SWAP,16)
	v_add_f32_e32 v133, v146, v147
	v_add_f32_e32 v134, v142, v143
	s_waitcnt lgkmcnt(0)
	v_add_f32_e32 v0, v0, v132
	v_add_f32_e32 v132, v144, v145
	v_add_f32_e32 v132, v132, v133
	v_add_f32_e32 v133, v140, v141
	v_add_f32_e32 v133, v133, v134
	v_add_f32_e32 v132, v132, v133
	ds_swizzle_b32 v133, v132 offset:swizzle(SWAP,16)
	v_add_f32_e32 v134, v150, v151
	v_mov_b32_e32 v138, v0
	s_nop 1
	v_permlane32_swap_b32_e32 v0, v138
	s_waitcnt lgkmcnt(0)
	v_add_f32_e32 v139, v132, v133
	v_add_f32_e32 v132, v152, v153
	v_add_f32_e32 v133, v154, v155
	v_add_f32_e32 v132, v132, v133
	v_add_f32_e32 v133, v148, v149
	v_add_f32_e32 v133, v133, v134
	v_add_f32_e32 v132, v132, v133
	ds_swizzle_b32 v133, v132 offset:swizzle(SWAP,16)
	v_add_f32_e32 v134, v158, v159
	v_mov_b32_e32 v140, v139
	s_nop 1
	v_permlane32_swap_b32_e32 v139, v140
	s_waitcnt lgkmcnt(0)
	v_add_f32_e32 v141, v132, v133
	v_add_f32_e32 v132, v160, v161
	v_add_f32_e32 v133, v162, v163
	v_add_f32_e32 v132, v132, v133
	v_add_f32_e32 v133, v156, v157
	v_add_f32_e32 v133, v133, v134
	v_add_f32_e32 v132, v132, v133
	ds_swizzle_b32 v133, v132 offset:swizzle(SWAP,16)
	v_mov_b32_e32 v142, v141
	s_nop 1
	v_permlane32_swap_b32_e32 v141, v142
	s_waitcnt lgkmcnt(0)
	v_add_f32_e32 v143, v132, v133
	v_lshl_add_u64 v[132:133], v[130:131], 0, s[0:1]
	s_movk_i32 s0, 0x4000
	v_add_co_u32_e32 v134, vcc, s0, v130
	s_movk_i32 s0, 0x5000
	s_nop 0
	v_addc_co_u32_e32 v135, vcc, 0, v131, vcc
	v_add_co_u32_e32 v136, vcc, s0, v130
	s_mov_b64 s[0:1], 0x4800
	s_nop 0
	v_addc_co_u32_e32 v137, vcc, 0, v131, vcc
	global_load_dwordx4 v[146:149], v[136:137], off offset:-4096
	global_load_dwordx4 v[150:153], v[132:133], off offset:16
	v_lshl_add_u64 v[132:133], v[130:131], 0, s[0:1]
	s_mov_b64 s[0:1], 0x5000
	global_load_dwordx4 v[154:157], v[134:135], off offset:2048
	global_load_dwordx4 v[158:161], v[132:133], off offset:16
	v_lshl_add_u64 v[132:133], v[130:131], 0, s[0:1]
	s_mov_b64 s[0:1], 0x5800
	v_lshl_add_u64 v[130:131], v[130:131], 0, s[0:1]
	global_load_dwordx4 v[162:165], v[136:137], off
	global_load_dwordx4 v[166:169], v[132:133], off offset:16
	s_nop 0
	global_load_dwordx4 v[134:137], v[136:137], off offset:2048
	s_nop 0
	global_load_dwordx4 v[130:133], v[130:131], off offset:16
	v_mov_b32_e32 v144, v143
	s_nop 1
	v_permlane32_swap_b32_e32 v143, v144
	s_waitcnt vmcnt(7)
	v_add_f32_e32 v145, v146, v147
	v_add_f32_e32 v146, v148, v149
	v_add_f32_e32 v145, v145, v146
	s_waitcnt vmcnt(6)
	v_add_f32_e32 v146, v150, v151
	v_add_f32_e32 v147, v152, v153
	v_add_f32_e32 v146, v146, v147
	s_waitcnt vmcnt(5)
	v_add_f32_e32 v147, v154, v155
	v_add_f32_e32 v148, v156, v157
	v_add_f32_e32 v147, v147, v148
	s_waitcnt vmcnt(4)
	v_add_f32_e32 v148, v158, v159
	v_add_f32_e32 v149, v160, v161
	v_add_f32_e32 v148, v148, v149
	s_waitcnt vmcnt(3)
	v_add_f32_e32 v149, v162, v163
	v_add_f32_e32 v150, v164, v165
	v_add_f32_e32 v149, v149, v150
	s_waitcnt vmcnt(2)
	v_add_f32_e32 v150, v166, v167
	v_add_f32_e32 v151, v168, v169
	s_waitcnt vmcnt(1)
	v_add_f32_e32 v134, v134, v135
	v_add_f32_e32 v135, v136, v137
	s_waitcnt vmcnt(0)
	v_add_f32_e32 v130, v130, v131
	v_add_f32_e32 v131, v132, v133
	v_add_f32_e32 v150, v150, v151
	v_add_f32_e32 v134, v134, v135
	v_add_f32_e32 v130, v130, v131
	v_add_f32_e32 v145, v145, v146
	v_add_f32_e32 v147, v147, v148
	v_add_f32_e32 v149, v149, v150
	v_add_f32_e32 v130, v134, v130
	ds_swizzle_b32 v146, v145 offset:swizzle(SWAP,16)
	ds_swizzle_b32 v148, v147 offset:swizzle(SWAP,16)
	ds_swizzle_b32 v150, v149 offset:swizzle(SWAP,16)
	ds_swizzle_b32 v131, v130 offset:swizzle(SWAP,16)
	s_waitcnt lgkmcnt(3)
	v_add_f32_e32 v145, v145, v146
	s_waitcnt lgkmcnt(2)
	v_add_f32_e32 v147, v147, v148
	s_waitcnt lgkmcnt(1)
	v_add_f32_e32 v149, v149, v150
	s_waitcnt lgkmcnt(0)
	v_add_f32_e32 v130, v130, v131
	v_mov_b32_e32 v146, v145
	v_mov_b32_e32 v148, v147
	v_mov_b32_e32 v150, v149
	v_mov_b32_e32 v131, v130
	v_permlane32_swap_b32_e32 v145, v146
	v_permlane32_swap_b32_e32 v147, v148
	v_permlane32_swap_b32_e32 v149, v150
	v_permlane32_swap_b32_e32 v130, v131
	s_and_saveexec_b64 s[0:1], s[4:5]
	s_cbranch_execz .LBB0_340
	v_add_f32_e32 v136, v139, v140
	v_add_f32_e32 v0, v0, v138
	v_add_f32_e32 v132, v147, v148
	v_add_f32_e32 v133, v145, v146
	v_fmamk_f32 v136, v136, 0x3a000000, v242
	v_fmamk_f32 v0, v0, 0x3a000000, v242
	v_fmamk_f32 v132, v132, 0x3a000000, v242
	v_fmamk_f32 v133, v133, 0x3a000000, v242
	v_add_f32_e32 v134, v143, v144
	v_add_f32_e32 v135, v141, v142
	v_rsq_f32_e32 v136, v136
	v_rsq_f32_e32 v0, v0
	v_add_f32_e32 v130, v130, v131
	v_add_f32_e32 v131, v149, v150
	v_rsq_f32_e32 v132, v132
	v_rsq_f32_e32 v133, v133
	v_fmamk_f32 v134, v134, 0x3a000000, v242
	v_fmamk_f32 v135, v135, 0x3a000000, v242
	v_fmamk_f32 v130, v130, 0x3a000000, v242
	v_fmamk_f32 v131, v131, 0x3a000000, v242
	v_rsq_f32_e32 v134, v134
	v_rsq_f32_e32 v135, v135
	v_rsq_f32_e32 v130, v130
	v_rsq_f32_e32 v131, v131
	ds_write2_b32 v222, v0, v136 offset1:16
	ds_write2_b32 v222, v133, v132 offset0:64 offset1:80
	ds_write2_b32 v222, v135, v134 offset0:32 offset1:48
	ds_write2_b32 v222, v131, v130 offset0:96 offset1:112

; #define PG8_STAGE(bufoff, gbase, voff) do { _Pragma("unroll") for (int _i = 0; _i < 2; ++_i) \
;         __builtin_amdgcn_global_load_lds((const unsigned*)((const char*)(gbase) + (voff)[_i]), (LAS unsigned*)(lds + (bufoff) + ldsw + _i * 8192), 16, 0, 0); } while (0)
; #define PG8_LDA(dst, b, h) do { _Pragma("unroll") for (int m = 0; m < 4; ++m) _Pragma("unroll") for (int k = 0; k < 2; ++k) dst[m][k] = *(const LAS bf16x8*)(lds + PG8_SA(b, h) + aoff + m * 2048 + k * 1024); } while (0)
; #define PG8_LDB(dst, b, h) do { _Pragma("unroll") for (int n = 0; n < 2; ++n) _Pragma("unroll") for (int k = 0; k < 2; ++k) dst[n][k] = *(const LAS bf16x8*)(lds + PG8_SB(b, h) + boff + n * 2048 + k * 1024); } while (0)
; #define PG8_WAIT_V(n) asm volatile("s_waitcnt vmcnt(" #n ")" ::: "memory")
; #define PG8_WAIT_L(n) asm volatile("s_waitcnt lgkmcnt(" #n ")" ::: "memory")
; #define PG8_BAR __builtin_amdgcn_s_barrier()
; #define PG8_SCHED __builtin_amdgcn_sched_barrier(0)
; template <class Epi>
; __device__ __forceinline__ void gemm_phase(const int tid, LAS unsigned char* lds, const Gemm g, const StaticOrder& S, const Epi& E) {
;     ...
;             PG8_LDB(B0, 0, 0); PG8_SCHED; PG8_LDA(At, 0, 0);
;             PG8_WAIT_L(8); PG8_BAR; PG8_WAIT_L(0); PG8_MMA(0, 0, At, B0); PG8_BAR; PG8_SCHED;
;             PG8_LDB(B1, 0, 1); PG8_STAGE(PG8_SB(0, 0), b2, voffB);
;             PG8_BAR; PG8_WAIT_L(0); PG8_MMA(0, 1, At, B1); PG8_BAR;
;             PG8_LDA(At, 0, 1); PG8_STAGE(PG8_SA(0, 0), a2, voffA);
;             PG8_BAR; PG8_WAIT_L(0); PG8_MMA(1, 0, At, B0); PG8_BAR; PG8_SCHED;
;             PG8_STAGE(PG8_SB(0, 1), b2 + hstep, voffB);
;             { const int first_ = __builtin_amdgcn_readfirstlane((ui > 0 && t == 0) ? 1 : 0);
;               if constexpr (Epi::SMIN == 8) asm volatile("s_cmp_eq_u32 %0, 0\n\ts_cbranch_scc1 .Lws_a%=\n\ts_waitcnt vmcnt(14)\n\ts_branch .Lws_b%=\n.Lws_a%=:\n\ts_waitcnt vmcnt(6)\n.Lws_b%=:" :: "s"(first_) : "memory", "scc");
;               else if constexpr (Epi::SMIN == 24) asm volatile("s_cmp_eq_u32 %0, 0\n\ts_cbranch_scc1 .Lws_a%=\n\ts_waitcnt vmcnt(30)\n\ts_branch .Lws_b%=\n.Lws_a%=:\n\ts_waitcnt vmcnt(6)\n.Lws_b%=:" :: "s"(first_) : "memory", "scc");
;               else PG8_WAIT_V(6); }
;             PG8_BAR; PG8_MMA(1, 1, At, B1); PG8_BAR;
.LBB0_419:
	s_add_i32 s68, 0, 0x10000
	v_add_u32_e32 v134, s68, v246
	ds_read_b128 v[106:109], v134
	ds_read_b128 v[110:113], v134 offset:1024
	ds_read_b128 v[122:125], v134 offset:2048
	ds_read_b128 v[134:137], v134 offset:3072
	s_add_i32 s67, s66, 2
	s_cmp_eq_u32 s54, s66
	s_cselect_b32 s15, s9, s61
	s_cselect_b32 s14, s8, s60
	s_cselect_b32 s17, s11, s65
	s_cselect_b32 s16, s10, s64
	ds_read_b128 v[138:141], v248
	ds_read_b128 v[142:145], v248 offset:1024
	ds_read_b128 v[146:149], v248 offset:2048
	ds_read_b128 v[150:153], v248 offset:3072
	ds_read_b128 v[154:157], v248 offset:4096
	ds_read_b128 v[158:161], v248 offset:5120
	ds_read_b128 v[162:165], v248 offset:6144
	ds_read_b128 v[174:177], v248 offset:7168
	s_waitcnt lgkmcnt(8)
	s_barrier
	s_setprio 1
	s_waitcnt lgkmcnt(7)
	v_mfma_f32_16x16x32_bf16 v[170:173], v[106:109], v[138:141], v[170:173]
	v_mfma_f32_16x16x32_bf16 v[166:169], v[122:125], v[138:141], v[166:169]
	s_waitcnt lgkmcnt(5)
	v_mfma_f32_16x16x32_bf16 v[118:121], v[106:109], v[146:149], v[118:121]
	v_mfma_f32_16x16x32_bf16 v[114:117], v[122:125], v[146:149], v[114:117]
	s_waitcnt lgkmcnt(3)
	v_mfma_f32_16x16x32_bf16 v[94:97], v[106:109], v[154:157], v[94:97]
	v_mfma_f32_16x16x32_bf16 v[90:93], v[122:125], v[154:157], v[90:93]
	s_waitcnt lgkmcnt(1)
	v_mfma_f32_16x16x32_bf16 v[78:81], v[106:109], v[162:165], v[78:81]
	v_mfma_f32_16x16x32_bf16 v[74:77], v[122:125], v[162:165], v[74:77]
	v_mfma_f32_16x16x32_bf16 v[170:173], v[110:113], v[142:145], v[170:173]
	v_mfma_f32_16x16x32_bf16 v[166:169], v[134:137], v[142:145], v[166:169]
	v_mfma_f32_16x16x32_bf16 v[118:121], v[110:113], v[150:153], v[118:121]
	v_mfma_f32_16x16x32_bf16 v[114:117], v[134:137], v[150:153], v[114:117]
	v_mfma_f32_16x16x32_bf16 v[94:97], v[110:113], v[158:161], v[94:97]
	v_mfma_f32_16x16x32_bf16 v[90:93], v[134:137], v[158:161], v[90:93]
	s_waitcnt lgkmcnt(0)
	v_mfma_f32_16x16x32_bf16 v[78:81], v[110:113], v[174:177], v[78:81]
	v_mfma_f32_16x16x32_bf16 v[74:77], v[134:137], v[174:177], v[74:77]
	s_setprio 0
	s_barrier
	s_add_i32 s69, 0, 0x14000
	s_add_i32 s68, s68, s28
	v_add_u32_e32 v190, s69, v246
	v_lshl_add_u64 v[204:205], s[16:17], 0, v[0:1]
	s_mov_b32 m0, s68
	ds_read_b128 v[178:181], v190
	ds_read_b128 v[182:185], v190 offset:1024
	ds_read_b128 v[186:189], v190 offset:2048
	ds_read_b128 v[190:193], v190 offset:3072
	global_load_lds_dwordx4 v[204:205], off
	v_lshl_add_u64 v[206:207], s[16:17], 0, v[194:195]
	s_add_i32 m0, s68, 0x2000
	s_nop 0
	global_load_lds_dwordx4 v[206:207], off
	s_barrier
	s_setprio 1
	s_waitcnt lgkmcnt(3)
	v_mfma_f32_16x16x32_bf16 v[130:133], v[178:181], v[138:141], v[130:133]
	s_waitcnt lgkmcnt(1)
	v_mfma_f32_16x16x32_bf16 v[126:129], v[186:189], v[138:141], v[126:129]
	v_mfma_f32_16x16x32_bf16 v[102:105], v[178:181], v[146:149], v[102:105]
	v_mfma_f32_16x16x32_bf16 v[98:101], v[186:189], v[146:149], v[98:101]
	v_mfma_f32_16x16x32_bf16 v[86:89], v[178:181], v[154:157], v[86:89]
	v_mfma_f32_16x16x32_bf16 v[82:85], v[186:189], v[154:157], v[82:85]
	v_mfma_f32_16x16x32_bf16 v[70:73], v[178:181], v[162:165], v[70:73]
	v_mfma_f32_16x16x32_bf16 v[66:69], v[186:189], v[162:165], v[66:69]
	v_mfma_f32_16x16x32_bf16 v[130:133], v[182:185], v[142:145], v[130:133]
	s_waitcnt lgkmcnt(0)
	v_mfma_f32_16x16x32_bf16 v[126:129], v[190:193], v[142:145], v[126:129]
	v_mfma_f32_16x16x32_bf16 v[102:105], v[182:185], v[150:153], v[102:105]
	v_mfma_f32_16x16x32_bf16 v[98:101], v[190:193], v[150:153], v[98:101]
	v_mfma_f32_16x16x32_bf16 v[86:89], v[182:185], v[158:161], v[86:89]
	v_mfma_f32_16x16x32_bf16 v[82:85], v[190:193], v[158:161], v[82:85]
	v_mfma_f32_16x16x32_bf16 v[70:73], v[182:185], v[174:177], v[70:73]
	v_mfma_f32_16x16x32_bf16 v[66:69], v[190:193], v[174:177], v[66:69]
	s_setprio 0
	s_mov_b32 m0, s36
	v_lshl_add_u64 v[208:209], s[14:15], 0, v[198:199]
	s_barrier
	ds_read_b128 v[138:141], v248 offset:16384
	ds_read_b128 v[142:145], v248 offset:17408
	ds_read_b128 v[146:149], v248 offset:18432
	ds_read_b128 v[150:153], v248 offset:19456
	ds_read_b128 v[154:157], v248 offset:20480
	ds_read_b128 v[158:161], v248 offset:21504
	ds_read_b128 v[162:165], v248 offset:22528
	ds_read_b128 v[174:177], v248 offset:23552
	global_load_lds_dwordx4 v[208:209], off
	v_lshl_add_u64 v[210:211], s[14:15], 0, v[196:197]
	s_mov_b32 m0, s37
	s_nop 0
	global_load_lds_dwordx4 v[210:211], off
	s_barrier
	s_setprio 1
	s_waitcnt lgkmcnt(7)
	v_mfma_f32_16x16x32_bf16 v[62:65], v[106:109], v[138:141], v[62:65]
	v_mfma_f32_16x16x32_bf16 v[58:61], v[122:125], v[138:141], v[58:61]
	s_waitcnt lgkmcnt(5)
	v_mfma_f32_16x16x32_bf16 v[46:49], v[106:109], v[146:149], v[46:49]
	v_mfma_f32_16x16x32_bf16 v[42:45], v[122:125], v[146:149], v[42:45]
	s_waitcnt lgkmcnt(3)
	v_mfma_f32_16x16x32_bf16 v[30:33], v[106:109], v[154:157], v[30:33]
	v_mfma_f32_16x16x32_bf16 v[26:29], v[122:125], v[154:157], v[26:29]
	s_waitcnt lgkmcnt(1)
	v_mfma_f32_16x16x32_bf16 v[14:17], v[106:109], v[162:165], v[14:17]
	v_mfma_f32_16x16x32_bf16 v[10:13], v[122:125], v[162:165], v[10:13]
	v_mfma_f32_16x16x32_bf16 v[62:65], v[110:113], v[142:145], v[62:65]
	v_mfma_f32_16x16x32_bf16 v[58:61], v[134:137], v[142:145], v[58:61]
	v_mfma_f32_16x16x32_bf16 v[46:49], v[110:113], v[150:153], v[46:49]
	v_mfma_f32_16x16x32_bf16 v[42:45], v[134:137], v[150:153], v[42:45]
	v_mfma_f32_16x16x32_bf16 v[30:33], v[110:113], v[158:161], v[30:33]
	v_mfma_f32_16x16x32_bf16 v[26:29], v[134:137], v[158:161], v[26:29]
	s_waitcnt lgkmcnt(0)
	v_mfma_f32_16x16x32_bf16 v[14:17], v[110:113], v[174:177], v[14:17]
	v_mfma_f32_16x16x32_bf16 v[10:13], v[134:137], v[174:177], v[10:13]
	s_setprio 0
	s_barrier
	s_add_u32 s16, s16, s26
	s_addc_u32 s17, s17, 0
	s_add_i32 s68, s69, s28
	v_lshl_add_u64 v[212:213], s[16:17], 0, v[0:1]
	s_mov_b32 m0, s68
	v_lshl_add_u64 v[214:215], s[16:17], 0, v[194:195]
	global_load_lds_dwordx4 v[212:213], off
	s_add_i32 m0, s68, 0x2000
	s_cmp_eq_u32 s66, 0
	global_load_lds_dwordx4 v[214:215], off
	s_cselect_b64 s[16:17], -1, 0
	s_and_b64 s[16:17], s[12:13], s[16:17]
	v_cndmask_b32_e64 v106, 0, 1, s[16:17]
	s_nop 0
	v_readfirstlane_b32 s16, v106
	s_and_b32 s16, s16, 1
	s_cmp_eq_u32 s16, 0
	s_cbranch_scc1 .Lws_a0
	s_waitcnt vmcnt(30)
	s_branch .Lws_b0

; #define PG8_STAGE(bufoff, gbase, voff) do { _Pragma("unroll") for (int _i = 0; _i < 2; ++_i) \
;         __builtin_amdgcn_global_load_lds((const unsigned*)((const char*)(gbase) + (voff)[_i]), (LAS unsigned*)(lds + (bufoff) + ldsw + _i * 8192), 16, 0, 0); } while (0)
; #define PG8_LDA(dst, b, h) do { _Pragma("unroll") for (int m = 0; m < 4; ++m) _Pragma("unroll") for (int k = 0; k < 2; ++k) dst[m][k] = *(const LAS bf16x8*)(lds + PG8_SA(b, h) + aoff + m * 2048 + k * 1024); } while (0)
; #define PG8_LDB(dst, b, h) do { _Pragma("unroll") for (int n = 0; n < 2; ++n) _Pragma("unroll") for (int k = 0; k < 2; ++k) dst[n][k] = *(const LAS bf16x8*)(lds + PG8_SB(b, h) + boff + n * 2048 + k * 1024); } while (0)
; #define PG8_MMA(ai, bj, At, Bt) do { __builtin_amdgcn_s_setprio(1); _Pragma("unroll") for (int m = 0; m < 4; ++m) _Pragma("unroll") for (int n = 0; n < 2; ++n) _Pragma("unroll") for (int k = 0; k < 2; ++k) \
;         acc[ai][bj][m][n] = __builtin_amdgcn_mfma_f32_16x16x32_bf16(Bt[n][k], At[m][k], acc[ai][bj][m][n], 0, 0, 0); __builtin_amdgcn_s_setprio(0); } while (0)
; #define PG8_WAIT_L(n) asm volatile("s_waitcnt lgkmcnt(" #n ")" ::: "memory")
; #define PG8_BAR __builtin_amdgcn_s_barrier()
; #define PG8_SCHED __builtin_amdgcn_sched_barrier(0)
; template <class Epi>
; __device__ __forceinline__ void gemm_phase(const int tid, LAS unsigned char* lds, const Gemm g, const StaticOrder& S, const Epi& E) {
;     ...
;             PG8_BAR; PG8_MMA(1, 1, At, B1); PG8_BAR;
;             PG8_LDB(B0, 1, 0); PG8_SCHED; PG8_LDA(At, 1, 0); PG8_STAGE(PG8_SA(0, 1), a2 + hstep, voffA);
;             PG8_WAIT_L(8); PG8_BAR; PG8_WAIT_L(0); PG8_MMA(0, 0, At, B0); PG8_BAR; PG8_SCHED;
;             PG8_LDB(B1, 1, 1); PG8_STAGE(PG8_SB(1, 0), b3, voffB);
;             PG8_BAR; PG8_WAIT_L(0); PG8_MMA(0, 1, At, B1); PG8_BAR;
;             PG8_LDA(At, 1, 1); PG8_STAGE(PG8_SA(1, 0), a3, voffA);
;             PG8_BAR; PG8_WAIT_L(0); PG8_MMA(1, 0, At, B0); PG8_BAR; PG8_SCHED;
.Lws_b0:
	s_barrier
	s_setprio 1
	v_mfma_f32_16x16x32_bf16 v[54:57], v[178:181], v[138:141], v[54:57]
	v_mfma_f32_16x16x32_bf16 v[50:53], v[186:189], v[138:141], v[50:53]
	v_mfma_f32_16x16x32_bf16 v[38:41], v[178:181], v[146:149], v[38:41]
	v_mfma_f32_16x16x32_bf16 v[34:37], v[186:189], v[146:149], v[34:37]
	v_mfma_f32_16x16x32_bf16 v[22:25], v[178:181], v[154:157], v[22:25]
	v_mfma_f32_16x16x32_bf16 v[18:21], v[186:189], v[154:157], v[18:21]
	v_mfma_f32_16x16x32_bf16 v[6:9], v[178:181], v[162:165], v[6:9]
	v_mfma_f32_16x16x32_bf16 v[2:5], v[186:189], v[162:165], v[2:5]
	v_mfma_f32_16x16x32_bf16 v[54:57], v[182:185], v[142:145], v[54:57]
	v_mfma_f32_16x16x32_bf16 v[50:53], v[190:193], v[142:145], v[50:53]
	v_mfma_f32_16x16x32_bf16 v[38:41], v[182:185], v[150:153], v[38:41]
	v_mfma_f32_16x16x32_bf16 v[34:37], v[190:193], v[150:153], v[34:37]
	v_mfma_f32_16x16x32_bf16 v[22:25], v[182:185], v[158:161], v[22:25]
	v_mfma_f32_16x16x32_bf16 v[18:21], v[190:193], v[158:161], v[18:21]
	v_mfma_f32_16x16x32_bf16 v[6:9], v[182:185], v[174:177], v[6:9]
	v_mfma_f32_16x16x32_bf16 v[2:5], v[190:193], v[174:177], v[2:5]
	s_setprio 0
	s_add_i32 s16, 0, 0x18000
	v_add_u32_e32 v134, s16, v246
	s_barrier
	ds_read_b128 v[106:109], v134
	ds_read_b128 v[110:113], v134 offset:1024
	ds_read_b128 v[122:125], v134 offset:2048
	ds_read_b128 v[134:137], v134 offset:3072
	s_add_u32 s14, s14, s26
	s_addc_u32 s15, s15, 0
	s_mov_b32 m0, s38
	v_lshl_add_u64 v[216:217], s[14:15], 0, v[198:199]
	ds_read_b128 v[138:141], v248 offset:32768
	ds_read_b128 v[142:145], v248 offset:33792
	ds_read_b128 v[146:149], v248 offset:34816
	ds_read_b128 v[150:153], v248 offset:35840
	ds_read_b128 v[154:157], v248 offset:36864
	ds_read_b128 v[158:161], v248 offset:37888
	ds_read_b128 v[162:165], v248 offset:38912
	ds_read_b128 v[174:177], v248 offset:39936
	global_load_lds_dwordx4 v[216:217], off
	v_lshl_add_u64 v[218:219], s[14:15], 0, v[196:197]
	s_mov_b32 m0, s39
	s_nop 0
	global_load_lds_dwordx4 v[218:219], off
	s_waitcnt lgkmcnt(8)
	s_barrier
	s_setprio 1
	s_waitcnt lgkmcnt(7)
	v_mfma_f32_16x16x32_bf16 v[170:173], v[106:109], v[138:141], v[170:173]
	v_mfma_f32_16x16x32_bf16 v[166:169], v[122:125], v[138:141], v[166:169]
	s_waitcnt lgkmcnt(5)
	v_mfma_f32_16x16x32_bf16 v[118:121], v[106:109], v[146:149], v[118:121]
	v_mfma_f32_16x16x32_bf16 v[114:117], v[122:125], v[146:149], v[114:117]
	s_waitcnt lgkmcnt(3)
	v_mfma_f32_16x16x32_bf16 v[94:97], v[106:109], v[154:157], v[94:97]
	v_mfma_f32_16x16x32_bf16 v[90:93], v[122:125], v[154:157], v[90:93]
	s_waitcnt lgkmcnt(1)
	v_mfma_f32_16x16x32_bf16 v[78:81], v[106:109], v[162:165], v[78:81]
	v_mfma_f32_16x16x32_bf16 v[74:77], v[122:125], v[162:165], v[74:77]
	v_mfma_f32_16x16x32_bf16 v[170:173], v[110:113], v[142:145], v[170:173]
	v_mfma_f32_16x16x32_bf16 v[166:169], v[134:137], v[142:145], v[166:169]
	v_mfma_f32_16x16x32_bf16 v[118:121], v[110:113], v[150:153], v[118:121]
	v_mfma_f32_16x16x32_bf16 v[114:117], v[134:137], v[150:153], v[114:117]
	v_mfma_f32_16x16x32_bf16 v[94:97], v[110:113], v[158:161], v[94:97]
	v_mfma_f32_16x16x32_bf16 v[90:93], v[134:137], v[158:161], v[90:93]
	s_waitcnt lgkmcnt(0)
	v_mfma_f32_16x16x32_bf16 v[78:81], v[110:113], v[174:177], v[78:81]
	v_mfma_f32_16x16x32_bf16 v[74:77], v[134:137], v[174:177], v[74:77]
	s_setprio 0
	s_barrier
	s_add_i32 s14, 0, 0x1c000
	s_add_i32 s15, s16, s28
	v_add_u32_e32 v190, s14, v246
	v_lshl_add_u64 v[204:205], v[204:205], 0, s[86:87]
	s_mov_b32 m0, s15
	ds_read_b128 v[178:181], v190
	ds_read_b128 v[182:185], v190 offset:1024
	ds_read_b128 v[186:189], v190 offset:2048
	ds_read_b128 v[190:193], v190 offset:3072
	global_load_lds_dwordx4 v[204:205], off
	v_lshl_add_u64 v[204:205], v[206:207], 0, s[86:87]
	s_add_i32 m0, s15, 0x2000
	s_nop 0
	global_load_lds_dwordx4 v[204:205], off
	s_barrier
	s_setprio 1
	s_waitcnt lgkmcnt(3)
	v_mfma_f32_16x16x32_bf16 v[130:133], v[178:181], v[138:141], v[130:133]
	s_waitcnt lgkmcnt(1)
	v_mfma_f32_16x16x32_bf16 v[126:129], v[186:189], v[138:141], v[126:129]
	v_mfma_f32_16x16x32_bf16 v[102:105], v[178:181], v[146:149], v[102:105]
	v_mfma_f32_16x16x32_bf16 v[98:101], v[186:189], v[146:149], v[98:101]
	v_mfma_f32_16x16x32_bf16 v[86:89], v[178:181], v[154:157], v[86:89]
	v_mfma_f32_16x16x32_bf16 v[82:85], v[186:189], v[154:157], v[82:85]
	v_mfma_f32_16x16x32_bf16 v[70:73], v[178:181], v[162:165], v[70:73]
	v_mfma_f32_16x16x32_bf16 v[66:69], v[186:189], v[162:165], v[66:69]
	v_mfma_f32_16x16x32_bf16 v[130:133], v[182:185], v[142:145], v[130:133]
	s_waitcnt lgkmcnt(0)
	v_mfma_f32_16x16x32_bf16 v[126:129], v[190:193], v[142:145], v[126:129]
	v_mfma_f32_16x16x32_bf16 v[102:105], v[182:185], v[150:153], v[102:105]
	v_mfma_f32_16x16x32_bf16 v[98:101], v[190:193], v[150:153], v[98:101]
	v_mfma_f32_16x16x32_bf16 v[86:89], v[182:185], v[158:161], v[86:89]
	v_mfma_f32_16x16x32_bf16 v[82:85], v[190:193], v[158:161], v[82:85]
	v_mfma_f32_16x16x32_bf16 v[70:73], v[182:185], v[174:177], v[70:73]
	v_mfma_f32_16x16x32_bf16 v[66:69], v[190:193], v[174:177], v[66:69]
	s_setprio 0
	s_mov_b32 m0, s46
	v_lshl_add_u64 v[204:205], v[208:209], 0, s[86:87]
	s_barrier
	ds_read_b128 v[138:141], v248 offset:49152
	ds_read_b128 v[142:145], v248 offset:50176
	ds_read_b128 v[146:149], v248 offset:51200
	ds_read_b128 v[150:153], v248 offset:52224
	ds_read_b128 v[154:157], v248 offset:53248
	ds_read_b128 v[158:161], v248 offset:54272
	ds_read_b128 v[162:165], v248 offset:55296
	ds_read_b128 v[174:177], v248 offset:56320
	global_load_lds_dwordx4 v[204:205], off
	v_lshl_add_u64 v[204:205], v[210:211], 0, s[86:87]
	s_mov_b32 m0, s47
	s_nop 0
	global_load_lds_dwordx4 v[204:205], off
	s_barrier
; #define PG8_STAGE(bufoff, gbase, voff) do { _Pragma("unroll") for (int _i = 0; _i < 2; ++_i) \
;         __builtin_amdgcn_global_load_lds((const unsigned*)((const char*)(gbase) + (voff)[_i]), (LAS unsigned*)(lds + (bufoff) + ldsw + _i * 8192), 16, 0, 0); } while (0)
; #define PG8_MMA(ai, bj, At, Bt) do { __builtin_amdgcn_s_setprio(1); _Pragma("unroll") for (int m = 0; m < 4; ++m) _Pragma("unroll") for (int n = 0; n < 2; ++n) _Pragma("unroll") for (int k = 0; k < 2; ++k) \
;         acc[ai][bj][m][n] = __builtin_amdgcn_mfma_f32_16x16x32_bf16(Bt[n][k], At[m][k], acc[ai][bj][m][n], 0, 0, 0); __builtin_amdgcn_s_setprio(0); } while (0)
; #define PG8_WAIT_V(n) asm volatile("s_waitcnt vmcnt(" #n ")" ::: "memory")
; #define PG8_WAIT_L(n) asm volatile("s_waitcnt lgkmcnt(" #n ")" ::: "memory")
; #define PG8_BAR __builtin_amdgcn_s_barrier()
; #define PG8_SCHED __builtin_amdgcn_sched_barrier(0)
; template <class Epi>
; __device__ __forceinline__ void gemm_phase(const int tid, LAS unsigned char* lds, const Gemm g, const StaticOrder& S, const Epi& E) {
;     ...
;             PG8_BAR; PG8_WAIT_L(0); PG8_MMA(1, 0, At, B0); PG8_BAR; PG8_SCHED;
;             PG8_STAGE(PG8_SB(1, 1), b3 + hstep, voffB);
;             PG8_WAIT_V(6); PG8_BAR; PG8_STAGE(PG8_SA(1, 1), a3 + hstep, voffA);
;             PG8_MMA(1, 1, At, B1); PG8_BAR;
;         }
	s_setprio 1
	s_waitcnt lgkmcnt(7)
	v_mfma_f32_16x16x32_bf16 v[62:65], v[106:109], v[138:141], v[62:65]
	v_mfma_f32_16x16x32_bf16 v[58:61], v[122:125], v[138:141], v[58:61]
	s_waitcnt lgkmcnt(5)
	v_mfma_f32_16x16x32_bf16 v[46:49], v[106:109], v[146:149], v[46:49]
	v_mfma_f32_16x16x32_bf16 v[42:45], v[122:125], v[146:149], v[42:45]
	s_waitcnt lgkmcnt(3)
	v_mfma_f32_16x16x32_bf16 v[30:33], v[106:109], v[154:157], v[30:33]
	v_mfma_f32_16x16x32_bf16 v[26:29], v[122:125], v[154:157], v[26:29]
	s_waitcnt lgkmcnt(1)
	v_mfma_f32_16x16x32_bf16 v[14:17], v[106:109], v[162:165], v[14:17]
	v_mfma_f32_16x16x32_bf16 v[10:13], v[122:125], v[162:165], v[10:13]
	v_mfma_f32_16x16x32_bf16 v[62:65], v[110:113], v[142:145], v[62:65]
	v_mfma_f32_16x16x32_bf16 v[58:61], v[134:137], v[142:145], v[58:61]
	v_mfma_f32_16x16x32_bf16 v[46:49], v[110:113], v[150:153], v[46:49]
	v_mfma_f32_16x16x32_bf16 v[42:45], v[134:137], v[150:153], v[42:45]
	v_mfma_f32_16x16x32_bf16 v[30:33], v[110:113], v[158:161], v[30:33]
	v_mfma_f32_16x16x32_bf16 v[26:29], v[134:137], v[158:161], v[26:29]
	s_waitcnt lgkmcnt(0)
	v_mfma_f32_16x16x32_bf16 v[14:17], v[110:113], v[174:177], v[14:17]
	v_mfma_f32_16x16x32_bf16 v[10:13], v[134:137], v[174:177], v[10:13]
	s_setprio 0
	s_barrier
	s_add_i32 s14, s14, s28
	v_lshl_add_u64 v[106:107], v[212:213], 0, s[86:87]
	s_mov_b32 m0, s14
	s_nop 0
	global_load_lds_dwordx4 v[106:107], off
	v_lshl_add_u64 v[106:107], v[214:215], 0, s[86:87]
	s_add_i32 m0, s14, 0x2000
	s_nop 0
	global_load_lds_dwordx4 v[106:107], off
	v_lshl_add_u64 v[106:107], v[216:217], 0, s[86:87]
	s_mov_b32 m0, s48
	s_waitcnt vmcnt(6)
	s_barrier
	global_load_lds_dwordx4 v[106:107], off
	v_lshl_add_u64 v[106:107], v[218:219], 0, s[86:87]
	s_mov_b32 m0, s49
	s_nop 0
	global_load_lds_dwordx4 v[106:107], off
	s_setprio 1
	v_mfma_f32_16x16x32_bf16 v[54:57], v[178:181], v[138:141], v[54:57]
	v_mfma_f32_16x16x32_bf16 v[50:53], v[186:189], v[138:141], v[50:53]
	v_mfma_f32_16x16x32_bf16 v[38:41], v[178:181], v[146:149], v[38:41]
	v_mfma_f32_16x16x32_bf16 v[34:37], v[186:189], v[146:149], v[34:37]
	v_mfma_f32_16x16x32_bf16 v[22:25], v[178:181], v[154:157], v[22:25]
	v_mfma_f32_16x16x32_bf16 v[18:21], v[186:189], v[154:157], v[18:21]
	v_mfma_f32_16x16x32_bf16 v[6:9], v[178:181], v[162:165], v[6:9]
	v_mfma_f32_16x16x32_bf16 v[2:5], v[186:189], v[162:165], v[2:5]
	v_mfma_f32_16x16x32_bf16 v[54:57], v[182:185], v[142:145], v[54:57]
	v_mfma_f32_16x16x32_bf16 v[50:53], v[190:193], v[142:145], v[50:53]
	v_mfma_f32_16x16x32_bf16 v[38:41], v[182:185], v[150:153], v[38:41]
	v_mfma_f32_16x16x32_bf16 v[34:37], v[190:193], v[150:153], v[34:37]
	v_mfma_f32_16x16x32_bf16 v[22:25], v[182:185], v[158:161], v[22:25]
	v_mfma_f32_16x16x32_bf16 v[18:21], v[190:193], v[158:161], v[18:21]
	v_mfma_f32_16x16x32_bf16 v[6:9], v[182:185], v[174:177], v[6:9]
	v_mfma_f32_16x16x32_bf16 v[2:5], v[190:193], v[174:177], v[2:5]
	s_setprio 0
	s_add_u32 s60, s60, 0x100
	s_addc_u32 s61, s61, 0
	s_add_u32 s64, s64, 0x100
	s_addc_u32 s65, s65, 0
	s_cmp_ge_u32 s67, s51
	s_mov_b32 s66, s67
	s_barrier
	s_cbranch_scc0 .LBB0_419
; __device__ __forceinline__ unsigned cvtpk(float lo, float hi) { unsigned r; asm volatile("v_cvt_pk_bf16_f32 %0, %1, %2" : "=v"(r) : "v"(lo), "v"(hi)); return r; }
; __device__ __forceinline__ float bflo(unsigned w) { return __uint_as_float(w << 16); }
; __device__ __forceinline__ float bfhi(unsigned w) { return __uint_as_float(w & 0xffff0000u); }
;     __device__ __forceinline__ void operator()(const AccT& acc, const pg8::Unit& u, int wr, int wc, int fr, int fq, pg8::RsCache& rsc) const {
;         const int row0 = u.pm * 256 + wr * 64 + fr, col0 = u.pn * 256 + wc * 32 + 8 * fq;
;         u32x4 xv[2][4][2];
; #pragma unroll
;         for (int ai = 0; ai < 2; ++ai)
; #pragma unroll
;             for (int m = 0; m < 4; ++m)
; #pragma unroll
;                 for (int bj = 0; bj < 2; ++bj) xv[ai][m][bj] = *(const u32x4*)(XB + (size_t)(row0 + ai * 128 + m * 16) * DM + col0 + bj * 128);
;         asm volatile("" ::: "memory");
; #pragma unroll
;         for (int ai = 0; ai < 2; ++ai) {
; #pragma unroll
;             for (int m = 0; m < 4; ++m) {
;                 const int row = row0 + ai * 128 + m * 16; float ss = 0.f;
; #pragma unroll
;                 for (int bj = 0; bj < 2; ++bj) {
;                     const u32x4 xx = xv[ai][m][bj]; const f32x4 a0 = acc[ai][bj][m][0] * scale, a1 = acc[ai][bj][m][1] * scale;
;                     const float y0 = bflo(xx.x) + a0[0], y1 = bfhi(xx.x) + a0[1], y2 = bflo(xx.y) + a0[2], y3 = bfhi(xx.y) + a0[3];
;                     const float y4 = bflo(xx.z) + a1[0], y5 = bfhi(xx.z) + a1[1], y6 = bflo(xx.w) + a1[2], y7 = bfhi(xx.w) + a1[3];
;                     u32x4 w; w.x = cvtpk(y0, y1); w.y = cvtpk(y2, y3); w.z = cvtpk(y4, y5); w.w = cvtpk(y6, y7);
;                     *(u32x4*)(XB + (size_t)row * DM + col0 + bj * 128) = w;
;                     ss += (y0 * y0 + y1 * y1) + (y2 * y2 + y3 * y3) + (y4 * y4 + y5 * y5) + (y6 * y6 + y7 * y7);
;                 }
;                 ss = xadd<16>(ss); ss = xadd<32>(ss);
;                 if (fq == 0) ssq_next[(size_t)row * 32 + u.pn * 4 + wc] = ss;
;             }
;         }
;     }
	v_lshl_or_b32 v206, s30, 8, v247
	v_lshl_add_u32 v234, s59, 8, v245
	v_ashrrev_i32_e32 v207, 31, v206
	v_lshlrev_b64 v[236:237], 1, v[206:207]
	v_ashrrev_i32_e32 v235, 31, v234
	v_lshl_add_u64 v[106:107], s[62:63], 0, v[236:237]
	v_lshlrev_b64 v[238:239], 12, v[234:235]
	v_lshl_add_u64 v[108:109], v[106:107], 0, v[238:239]
	global_load_dwordx4 v[190:193], v[108:109], off
	global_load_dwordx4 v[186:189], v[108:109], off offset:256
	v_or_b32_e32 v230, 16, v234
	v_ashrrev_i32_e32 v231, 31, v230
	v_or_b32_e32 v226, 32, v234
	v_lshlrev_b64 v[232:233], 12, v[230:231]
	v_ashrrev_i32_e32 v227, 31, v226
	v_or_b32_e32 v222, 48, v234
	v_lshl_add_u64 v[108:109], v[106:107], 0, v[232:233]
	v_lshlrev_b64 v[228:229], 12, v[226:227]
	v_ashrrev_i32_e32 v223, 31, v222
	v_add_u32_e32 v218, 0x80, v234
	global_load_dwordx4 v[182:185], v[108:109], off
	global_load_dwordx4 v[178:181], v[108:109], off offset:256
	v_lshl_add_u64 v[108:109], v[106:107], 0, v[228:229]
	v_lshlrev_b64 v[224:225], 12, v[222:223]
	v_ashrrev_i32_e32 v219, 31, v218
	v_add_u32_e32 v214, 0x90, v234
	global_load_dwordx4 v[174:177], v[108:109], off
	global_load_dwordx4 v[162:165], v[108:109], off offset:256
	v_lshl_add_u64 v[108:109], v[106:107], 0, v[224:225]
	v_lshlrev_b64 v[220:221], 12, v[218:219]
	v_ashrrev_i32_e32 v215, 31, v214
	v_add_u32_e32 v210, 0xa0, v234
	v_add_u32_e32 v204, 0xb0, v234
	global_load_dwordx4 v[158:161], v[108:109], off
	global_load_dwordx4 v[154:157], v[108:109], off offset:256
	v_lshl_add_u64 v[108:109], v[106:107], 0, v[220:221]
	v_lshlrev_b64 v[216:217], 12, v[214:215]
	v_ashrrev_i32_e32 v211, 31, v210
	v_ashrrev_i32_e32 v205, 31, v204
	global_load_dwordx4 v[150:153], v[108:109], off
	global_load_dwordx4 v[146:149], v[108:109], off offset:256
	v_lshl_add_u64 v[108:109], v[106:107], 0, v[216:217]
	v_lshlrev_b64 v[212:213], 12, v[210:211]
	v_lshlrev_b64 v[208:209], 12, v[204:205]
	global_load_dwordx4 v[142:145], v[108:109], off
	global_load_dwordx4 v[138:141], v[108:109], off offset:256
	v_lshl_add_u64 v[108:109], v[106:107], 0, v[212:213]
	v_lshl_add_u64 v[106:107], v[106:107], 0, v[208:209]
	global_load_dwordx4 v[134:137], v[108:109], off
	global_load_dwordx4 v[122:125], v[108:109], off offset:256
	global_load_dwordx4 v[110:113], v[106:107], off
	s_nop 0
	global_load_dwordx4 v[106:109], v[106:107], off offset:256
	v_pk_mul_f32 v[170:171], v[202:203], v[170:171]
	v_mov_b32_e32 v201, v200
	v_pk_mul_f32 v[172:173], v[200:201], v[172:173]
	v_pk_mul_f32 v[166:167], v[202:203], v[166:167]
	v_pk_mul_f32 v[168:169], v[200:201], v[168:169]
	v_pk_mul_f32 v[130:131], v[202:203], v[130:131]
	v_pk_mul_f32 v[132:133], v[200:201], v[132:133]
	v_pk_mul_f32 v[126:127], v[202:203], v[126:127]
	v_pk_mul_f32 v[128:129], v[200:201], v[128:129]
	s_lshl_b32 s12, s30, 2
	s_ashr_i32 s13, s12, 31
	s_waitcnt vmcnt(0)
	v_lshlrev_b32_e32 v240, 16, v190
	v_add_f32_e32 v240, v170, v240
	v_and_b32_e32 v170, 0xffff0000, v190
	v_add_f32_e32 v190, v171, v170
	v_lshlrev_b32_e32 v170, 16, v191
	v_add_f32_e32 v172, v172, v170
	v_and_b32_e32 v170, 0xffff0000, v191
	v_add_f32_e32 v173, v173, v170
	v_lshlrev_b32_e32 v170, 16, v192
	v_add_f32_e32 v191, v166, v170
	v_and_b32_e32 v166, 0xffff0000, v192
	v_add_f32_e32 v192, v167, v166
	v_lshlrev_b32_e32 v166, 16, v193
	v_add_f32_e32 v241, v168, v166
	v_and_b32_e32 v166, 0xffff0000, v193
	v_lshl_add_u64 v[170:171], s[62:63], 0, v[238:239]
	v_add_f32_e32 v193, v169, v166
	v_cvt_pk_bf16_f32 v166, v240, v190
	v_cvt_pk_bf16_f32 v167, v172, v173
	v_lshl_add_u64 v[170:171], v[170:171], 0, v[236:237]
	v_cvt_pk_bf16_f32 v168, v191, v192
	v_cvt_pk_bf16_f32 v169, v241, v193
	global_store_dwordx4 v[170:171], v[166:169], off
	s_nop 1
	v_mul_f32_e32 v166, v190, v190
	v_mul_f32_e32 v167, v173, v173
	v_fmac_f32_e32 v166, v240, v240
	v_fmac_f32_e32 v167, v172, v172
	v_add_f32_e32 v166, v166, v167
	v_mul_f32_e32 v167, v192, v192
	v_fmac_f32_e32 v167, v191, v191
	v_add_f32_e32 v166, v167, v166
	v_mul_f32_e32 v167, v193, v193
	v_fmac_f32_e32 v167, v241, v241
	v_add_f32_e32 v166, v167, v166
	v_lshlrev_b32_e32 v167, 16, v186
	v_add_f32_e32 v130, v130, v167
	v_and_b32_e32 v167, 0xffff0000, v186
	v_add_f32_e32 v131, v131, v167
	v_lshlrev_b32_e32 v167, 16, v187
	v_add_f32_e32 v132, v132, v167
	v_and_b32_e32 v167, 0xffff0000, v187
	v_add_f32_e32 v133, v133, v167
	v_lshlrev_b32_e32 v167, 16, v188
	v_add_f32_e32 v167, v126, v167
	v_and_b32_e32 v126, 0xffff0000, v188
	v_add_f32_e32 v168, v127, v126
	v_lshlrev_b32_e32 v126, 16, v189
	v_add_f32_e32 v169, v128, v126
	v_and_b32_e32 v126, 0xffff0000, v189
	v_add_f32_e32 v172, v129, v126
	v_cvt_pk_bf16_f32 v126, v130, v131
	v_cvt_pk_bf16_f32 v127, v132, v133
	v_cvt_pk_bf16_f32 v128, v167, v168
	v_cvt_pk_bf16_f32 v129, v169, v172
	global_store_dwordx4 v[170:171], v[126:129], off offset:256
	s_nop 1
	v_mul_f32_e32 v126, v131, v131
	v_mul_f32_e32 v127, v133, v133
	v_fmac_f32_e32 v126, v130, v130
	v_fmac_f32_e32 v127, v132, v132
	v_add_f32_e32 v126, v126, v127
	v_mul_f32_e32 v127, v168, v168
	v_fmac_f32_e32 v127, v167, v167
	v_add_f32_e32 v126, v127, v126
	v_mul_f32_e32 v127, v172, v172
	v_fmac_f32_e32 v127, v169, v169
	v_add_f32_e32 v126, v127, v126
	v_add_f32_e32 v126, v166, v126
	ds_swizzle_b32 v127, v126 offset:swizzle(SWAP,16)
	s_waitcnt lgkmcnt(0)
	v_add_f32_e32 v126, v126, v127
	v_mov_b32_e32 v127, v126
	s_nop 1
	v_permlane32_swap_b32_e32 v126, v127
	s_and_saveexec_b64 s[14:15], s[4:5]
	s_cbranch_execz .LBB0_422
	v_lshlrev_b64 v[128:129], 7, v[234:235]
	v_lshl_add_u64 v[128:129], s[0:1], 0, v[128:129]
	v_lshl_add_u64 v[128:129], s[12:13], 2, v[128:129]
	s_lshl_b32 s30, s50, 2
	v_lshl_add_u64 v[128:129], v[128:129], 0, s[30:31]
	v_add_f32_e32 v126, v126, v127
	global_store_dword v[128:129], v126, off

; #define PG8_STAGE(bufoff, gbase, voff) do { _Pragma("unroll") for (int _i = 0; _i < 2; ++_i) \
;         __builtin_amdgcn_global_load_lds((const unsigned*)((const char*)(gbase) + (voff)[_i]), (LAS unsigned*)(lds + (bufoff) + ldsw + _i * 8192), 16, 0, 0); } while (0)
; #define PG8_LDA(dst, b, h) do { _Pragma("unroll") for (int m = 0; m < 4; ++m) _Pragma("unroll") for (int k = 0; k < 2; ++k) dst[m][k] = *(const LAS bf16x8*)(lds + PG8_SA(b, h) + aoff + m * 2048 + k * 1024); } while (0)
; #define PG8_LDB(dst, b, h) do { _Pragma("unroll") for (int n = 0; n < 2; ++n) _Pragma("unroll") for (int k = 0; k < 2; ++k) dst[n][k] = *(const LAS bf16x8*)(lds + PG8_SB(b, h) + boff + n * 2048 + k * 1024); } while (0)
; #define PG8_MMA(ai, bj, At, Bt) do { __builtin_amdgcn_s_setprio(1); _Pragma("unroll") for (int m = 0; m < 4; ++m) _Pragma("unroll") for (int n = 0; n < 2; ++n) _Pragma("unroll") for (int k = 0; k < 2; ++k) \
;         acc[ai][bj][m][n] = __builtin_amdgcn_mfma_f32_16x16x32_bf16(Bt[n][k], At[m][k], acc[ai][bj][m][n], 0, 0, 0); __builtin_amdgcn_s_setprio(0); } while (0)
; #define PG8_BAR __builtin_amdgcn_s_barrier()
; template <class Epi>
; __device__ __forceinline__ void gemm_phase(const int tid, LAS unsigned char* lds, const Gemm g, const StaticOrder& S, const Epi& E) {
;     ...
;             PG8_LDB(B0, 0, 0); PG8_SCHED; PG8_LDA(At, 0, 0);
;             PG8_WAIT_L(8); PG8_BAR; PG8_WAIT_L(0); PG8_MMA(0, 0, At, B0); PG8_BAR; PG8_SCHED;
;             PG8_LDB(B1, 0, 1); PG8_STAGE(PG8_SB(0, 0), b2, voffB);
;             PG8_BAR; PG8_WAIT_L(0); PG8_MMA(0, 1, At, B1); PG8_BAR;
;             PG8_LDA(At, 0, 1); PG8_STAGE(PG8_SA(0, 0), a2, voffA);
;             PG8_BAR; PG8_WAIT_L(0); PG8_MMA(1, 0, At, B0); PG8_BAR; PG8_SCHED;
;             PG8_STAGE(PG8_SB(0, 1), b2 + hstep, voffB);
;             { const int first_ = __builtin_amdgcn_readfirstlane((ui > 0 && t == 0) ? 1 : 0);
;               if constexpr (Epi::SMIN == 8) asm volatile("s_cmp_eq_u32 %0, 0\n\ts_cbranch_scc1 .Lws_a%=\n\ts_waitcnt vmcnt(14)\n\ts_branch .Lws_b%=\n.Lws_a%=:\n\ts_waitcnt vmcnt(6)\n.Lws_b%=:" :: "s"(first_) : "memory", "scc");
;               else if constexpr (Epi::SMIN == 24) asm volatile("s_cmp_eq_u32 %0, 0\n\ts_cbranch_scc1 .Lws_a%=\n\ts_waitcnt vmcnt(30)\n\ts_branch .Lws_b%=\n.Lws_a%=:\n\ts_waitcnt vmcnt(6)\n.Lws_b%=:" :: "s"(first_) : "memory", "scc");
;               else PG8_WAIT_V(6); }
.LBB0_448:
	s_add_i32 s66, 0, 0x10000
	v_add_u32_e32 v150, s66, v155
	ds_read_b128 v[130:133], v150
	ds_read_b128 v[142:145], v150 offset:1024
	ds_read_b128 v[146:149], v150 offset:2048
	ds_read_b128 v[150:153], v150 offset:3072
	s_cmp_eq_u32 s65, 28
	s_cselect_b32 s25, s13, s60
	s_cselect_b32 s24, s57, s59
	s_cselect_b32 s37, s11, s64
	s_cselect_b32 s36, s58, s61
	ds_read_b128 v[160:163], v158
	ds_read_b128 v[164:167], v158 offset:1024
	ds_read_b128 v[168:171], v158 offset:2048
	ds_read_b128 v[172:175], v158 offset:3072
	ds_read_b128 v[176:179], v158 offset:4096
	ds_read_b128 v[180:183], v158 offset:5120
	ds_read_b128 v[184:187], v158 offset:6144
	ds_read_b128 v[188:191], v158 offset:7168
	s_waitcnt lgkmcnt(8)
	s_barrier
	s_setprio 1
	s_waitcnt lgkmcnt(7)
	v_mfma_f32_16x16x32_bf16 v[126:129], v[130:133], v[160:163], v[126:129]
	v_mfma_f32_16x16x32_bf16 v[118:121], v[146:149], v[160:163], v[118:121]
	s_waitcnt lgkmcnt(5)
	v_mfma_f32_16x16x32_bf16 v[110:113], v[130:133], v[168:171], v[110:113]
	v_mfma_f32_16x16x32_bf16 v[102:105], v[146:149], v[168:171], v[102:105]
	s_waitcnt lgkmcnt(3)
	v_mfma_f32_16x16x32_bf16 v[94:97], v[130:133], v[176:179], v[94:97]
	v_mfma_f32_16x16x32_bf16 v[86:89], v[146:149], v[176:179], v[86:89]
	s_waitcnt lgkmcnt(1)
	v_mfma_f32_16x16x32_bf16 v[78:81], v[130:133], v[184:187], v[78:81]
	v_mfma_f32_16x16x32_bf16 v[70:73], v[146:149], v[184:187], v[70:73]
	v_mfma_f32_16x16x32_bf16 v[126:129], v[142:145], v[164:167], v[126:129]
	v_mfma_f32_16x16x32_bf16 v[118:121], v[150:153], v[164:167], v[118:121]
	v_mfma_f32_16x16x32_bf16 v[110:113], v[142:145], v[172:175], v[110:113]
	v_mfma_f32_16x16x32_bf16 v[102:105], v[150:153], v[172:175], v[102:105]
	v_mfma_f32_16x16x32_bf16 v[94:97], v[142:145], v[180:183], v[94:97]
	v_mfma_f32_16x16x32_bf16 v[86:89], v[150:153], v[180:183], v[86:89]
	s_waitcnt lgkmcnt(0)
	v_mfma_f32_16x16x32_bf16 v[78:81], v[142:145], v[188:191], v[78:81]
	v_mfma_f32_16x16x32_bf16 v[70:73], v[150:153], v[188:191], v[70:73]
	s_setprio 0
	s_barrier
	s_add_i32 s68, 0, 0x14000
	s_add_i32 s66, s66, s28
	v_add_u32_e32 v159, s68, v155
	v_lshl_add_u64 v[208:209], s[36:37], 0, v[0:1]
	s_mov_b32 m0, s66
	ds_read_b128 v[192:195], v159
	ds_read_b128 v[196:199], v159 offset:1024
	ds_read_b128 v[200:203], v159 offset:2048
	ds_read_b128 v[204:207], v159 offset:3072
	global_load_lds_dwordx4 v[208:209], off
	v_lshl_add_u64 v[210:211], s[36:37], 0, v[134:135]
	s_add_i32 m0, s66, 0x2000
	s_nop 0
	global_load_lds_dwordx4 v[210:211], off
	s_barrier
	s_setprio 1
	s_waitcnt lgkmcnt(3)
	v_mfma_f32_16x16x32_bf16 v[122:125], v[192:195], v[160:163], v[122:125]
	s_waitcnt lgkmcnt(1)
	v_mfma_f32_16x16x32_bf16 v[114:117], v[200:203], v[160:163], v[114:117]
	v_mfma_f32_16x16x32_bf16 v[106:109], v[192:195], v[168:171], v[106:109]
	v_mfma_f32_16x16x32_bf16 v[98:101], v[200:203], v[168:171], v[98:101]
	v_mfma_f32_16x16x32_bf16 v[90:93], v[192:195], v[176:179], v[90:93]
	v_mfma_f32_16x16x32_bf16 v[82:85], v[200:203], v[176:179], v[82:85]
	v_mfma_f32_16x16x32_bf16 v[74:77], v[192:195], v[184:187], v[74:77]
	v_mfma_f32_16x16x32_bf16 v[66:69], v[200:203], v[184:187], v[66:69]
	v_mfma_f32_16x16x32_bf16 v[122:125], v[196:199], v[164:167], v[122:125]
	s_waitcnt lgkmcnt(0)
	v_mfma_f32_16x16x32_bf16 v[114:117], v[204:207], v[164:167], v[114:117]
	v_mfma_f32_16x16x32_bf16 v[106:109], v[196:199], v[172:175], v[106:109]
	v_mfma_f32_16x16x32_bf16 v[98:101], v[204:207], v[172:175], v[98:101]
	v_mfma_f32_16x16x32_bf16 v[90:93], v[196:199], v[180:183], v[90:93]
	v_mfma_f32_16x16x32_bf16 v[82:85], v[204:207], v[180:183], v[82:85]
	v_mfma_f32_16x16x32_bf16 v[74:77], v[196:199], v[188:191], v[74:77]
	v_mfma_f32_16x16x32_bf16 v[66:69], v[204:207], v[188:191], v[66:69]
	s_setprio 0
	s_mov_b32 m0, s30
	v_lshl_add_u64 v[212:213], s[24:25], 0, v[138:139]
	s_barrier
	ds_read_b128 v[160:163], v158 offset:16384
	ds_read_b128 v[164:167], v158 offset:17408
	ds_read_b128 v[168:171], v158 offset:18432
	ds_read_b128 v[172:175], v158 offset:19456
	ds_read_b128 v[176:179], v158 offset:20480
	ds_read_b128 v[180:183], v158 offset:21504
	ds_read_b128 v[184:187], v158 offset:22528
	ds_read_b128 v[188:191], v158 offset:23552
	global_load_lds_dwordx4 v[212:213], off
	v_lshl_add_u64 v[214:215], s[24:25], 0, v[136:137]
	s_mov_b32 m0, s38
	s_nop 0
	global_load_lds_dwordx4 v[214:215], off
	s_barrier
	s_setprio 1
	s_waitcnt lgkmcnt(7)
	v_mfma_f32_16x16x32_bf16 v[62:65], v[130:133], v[160:163], v[62:65]
	v_mfma_f32_16x16x32_bf16 v[54:57], v[146:149], v[160:163], v[54:57]
	s_waitcnt lgkmcnt(5)
	v_mfma_f32_16x16x32_bf16 v[46:49], v[130:133], v[168:171], v[46:49]
	v_mfma_f32_16x16x32_bf16 v[38:41], v[146:149], v[168:171], v[38:41]
	s_waitcnt lgkmcnt(3)
	v_mfma_f32_16x16x32_bf16 v[30:33], v[130:133], v[176:179], v[30:33]
	v_mfma_f32_16x16x32_bf16 v[22:25], v[146:149], v[176:179], v[22:25]
	s_waitcnt lgkmcnt(1)
	v_mfma_f32_16x16x32_bf16 v[14:17], v[130:133], v[184:187], v[14:17]
	v_mfma_f32_16x16x32_bf16 v[6:9], v[146:149], v[184:187], v[6:9]
	v_mfma_f32_16x16x32_bf16 v[62:65], v[142:145], v[164:167], v[62:65]
	v_mfma_f32_16x16x32_bf16 v[54:57], v[150:153], v[164:167], v[54:57]
	v_mfma_f32_16x16x32_bf16 v[46:49], v[142:145], v[172:175], v[46:49]
	v_mfma_f32_16x16x32_bf16 v[38:41], v[150:153], v[172:175], v[38:41]
	v_mfma_f32_16x16x32_bf16 v[30:33], v[142:145], v[180:183], v[30:33]
	v_mfma_f32_16x16x32_bf16 v[22:25], v[150:153], v[180:183], v[22:25]
	s_waitcnt lgkmcnt(0)
	v_mfma_f32_16x16x32_bf16 v[14:17], v[142:145], v[188:191], v[14:17]
	v_mfma_f32_16x16x32_bf16 v[6:9], v[150:153], v[188:191], v[6:9]
	s_setprio 0
	s_barrier
	s_add_u32 s66, s36, 0x80000
	s_addc_u32 s67, s37, 0
	s_add_i32 s68, s68, s28
	v_lshl_add_u64 v[130:131], s[66:67], 0, v[0:1]
	s_mov_b32 m0, s68
	s_nop 0
	global_load_lds_dwordx4 v[130:131], off
	v_lshl_add_u64 v[130:131], s[66:67], 0, v[134:135]
	s_add_i32 m0, s68, 0x2000
	s_cmp_eq_u32 s65, -2
	global_load_lds_dwordx4 v[130:131], off
	s_cselect_b64 s[66:67], -1, 0
	s_and_b64 s[66:67], s[22:23], s[66:67]
	v_cndmask_b32_e64 v130, 0, 1, s[66:67]
	s_nop 0
	v_readfirstlane_b32 s66, v130
	s_and_b32 s66, s66, 1
	s_cmp_eq_u32 s66, 0
	s_cbranch_scc1 .Lws_a1
	s_waitcnt vmcnt(14)
	s_branch .Lws_b1

; #define PG8_STAGE(bufoff, gbase, voff) do { _Pragma("unroll") for (int _i = 0; _i < 2; ++_i) \
;         __builtin_amdgcn_global_load_lds((const unsigned*)((const char*)(gbase) + (voff)[_i]), (LAS unsigned*)(lds + (bufoff) + ldsw + _i * 8192), 16, 0, 0); } while (0)
; #define PG8_LDA(dst, b, h) do { _Pragma("unroll") for (int m = 0; m < 4; ++m) _Pragma("unroll") for (int k = 0; k < 2; ++k) dst[m][k] = *(const LAS bf16x8*)(lds + PG8_SA(b, h) + aoff + m * 2048 + k * 1024); } while (0)
; #define PG8_LDB(dst, b, h) do { _Pragma("unroll") for (int n = 0; n < 2; ++n) _Pragma("unroll") for (int k = 0; k < 2; ++k) dst[n][k] = *(const LAS bf16x8*)(lds + PG8_SB(b, h) + boff + n * 2048 + k * 1024); } while (0)
; #define PG8_MMA(ai, bj, At, Bt) do { __builtin_amdgcn_s_setprio(1); _Pragma("unroll") for (int m = 0; m < 4; ++m) _Pragma("unroll") for (int n = 0; n < 2; ++n) _Pragma("unroll") for (int k = 0; k < 2; ++k) \
;         acc[ai][bj][m][n] = __builtin_amdgcn_mfma_f32_16x16x32_bf16(Bt[n][k], At[m][k], acc[ai][bj][m][n], 0, 0, 0); __builtin_amdgcn_s_setprio(0); } while (0)
; #define PG8_WAIT_L(n) asm volatile("s_waitcnt lgkmcnt(" #n ")" ::: "memory")
; #define PG8_BAR __builtin_amdgcn_s_barrier()
; #define PG8_SCHED __builtin_amdgcn_sched_barrier(0)
; template <class Epi>
; __device__ __forceinline__ void gemm_phase(const int tid, LAS unsigned char* lds, const Gemm g, const StaticOrder& S, const Epi& E) {
;     ...
;             PG8_BAR; PG8_MMA(1, 1, At, B1); PG8_BAR;
;             PG8_LDB(B0, 1, 0); PG8_SCHED; PG8_LDA(At, 1, 0); PG8_STAGE(PG8_SA(0, 1), a2 + hstep, voffA);
;             PG8_WAIT_L(8); PG8_BAR; PG8_WAIT_L(0); PG8_MMA(0, 0, At, B0); PG8_BAR; PG8_SCHED;
;             PG8_LDB(B1, 1, 1); PG8_STAGE(PG8_SB(1, 0), b3, voffB);
;             PG8_BAR; PG8_WAIT_L(0); PG8_MMA(0, 1, At, B1); PG8_BAR;
;             PG8_LDA(At, 1, 1); PG8_STAGE(PG8_SA(1, 0), a3, voffA);
;             PG8_BAR; PG8_WAIT_L(0); PG8_MMA(1, 0, At, B0); PG8_BAR; PG8_SCHED;
.Lws_b1:
	s_barrier
	s_setprio 1
	v_mfma_f32_16x16x32_bf16 v[58:61], v[192:195], v[160:163], v[58:61]
	v_mfma_f32_16x16x32_bf16 v[50:53], v[200:203], v[160:163], v[50:53]
	v_mfma_f32_16x16x32_bf16 v[42:45], v[192:195], v[168:171], v[42:45]
	v_mfma_f32_16x16x32_bf16 v[34:37], v[200:203], v[168:171], v[34:37]
	v_mfma_f32_16x16x32_bf16 v[26:29], v[192:195], v[176:179], v[26:29]
	v_mfma_f32_16x16x32_bf16 v[18:21], v[200:203], v[176:179], v[18:21]
	v_mfma_f32_16x16x32_bf16 v[10:13], v[192:195], v[184:187], v[10:13]
	v_mfma_f32_16x16x32_bf16 v[2:5], v[200:203], v[184:187], v[2:5]
	v_mfma_f32_16x16x32_bf16 v[58:61], v[196:199], v[164:167], v[58:61]
	v_mfma_f32_16x16x32_bf16 v[50:53], v[204:207], v[164:167], v[50:53]
	v_mfma_f32_16x16x32_bf16 v[42:45], v[196:199], v[172:175], v[42:45]
	v_mfma_f32_16x16x32_bf16 v[34:37], v[204:207], v[172:175], v[34:37]
	v_mfma_f32_16x16x32_bf16 v[26:29], v[196:199], v[180:183], v[26:29]
	v_mfma_f32_16x16x32_bf16 v[18:21], v[204:207], v[180:183], v[18:21]
	v_mfma_f32_16x16x32_bf16 v[10:13], v[196:199], v[188:191], v[10:13]
	v_mfma_f32_16x16x32_bf16 v[2:5], v[204:207], v[188:191], v[2:5]
	s_setprio 0
	s_add_i32 s68, 0, 0x18000
	v_add_u32_e32 v150, s68, v155
	s_barrier
	ds_read_b128 v[130:133], v150
	ds_read_b128 v[142:145], v150 offset:1024
	ds_read_b128 v[146:149], v150 offset:2048
	ds_read_b128 v[150:153], v150 offset:3072
	s_add_u32 s66, s24, 0x80000
	s_addc_u32 s67, s25, 0
	s_mov_b32 m0, s39
	v_lshl_add_u64 v[192:193], s[66:67], 0, v[138:139]
	ds_read_b128 v[160:163], v158 offset:32768
	ds_read_b128 v[164:167], v158 offset:33792
	ds_read_b128 v[168:171], v158 offset:34816
	ds_read_b128 v[172:175], v158 offset:35840
	ds_read_b128 v[176:179], v158 offset:36864
	ds_read_b128 v[180:183], v158 offset:37888
	ds_read_b128 v[184:187], v158 offset:38912
	ds_read_b128 v[188:191], v158 offset:39936
	global_load_lds_dwordx4 v[192:193], off
	v_lshl_add_u64 v[192:193], s[66:67], 0, v[136:137]
	s_mov_b32 m0, s46
	s_nop 0
	global_load_lds_dwordx4 v[192:193], off
	s_waitcnt lgkmcnt(8)
	s_barrier
	s_setprio 1
	s_waitcnt lgkmcnt(7)
	v_mfma_f32_16x16x32_bf16 v[126:129], v[130:133], v[160:163], v[126:129]
	v_mfma_f32_16x16x32_bf16 v[118:121], v[146:149], v[160:163], v[118:121]
	s_waitcnt lgkmcnt(5)
	v_mfma_f32_16x16x32_bf16 v[110:113], v[130:133], v[168:171], v[110:113]
	v_mfma_f32_16x16x32_bf16 v[102:105], v[146:149], v[168:171], v[102:105]
	s_waitcnt lgkmcnt(3)
	v_mfma_f32_16x16x32_bf16 v[94:97], v[130:133], v[176:179], v[94:97]
	v_mfma_f32_16x16x32_bf16 v[86:89], v[146:149], v[176:179], v[86:89]
	s_waitcnt lgkmcnt(1)
	v_mfma_f32_16x16x32_bf16 v[78:81], v[130:133], v[184:187], v[78:81]
	v_mfma_f32_16x16x32_bf16 v[70:73], v[146:149], v[184:187], v[70:73]
	v_mfma_f32_16x16x32_bf16 v[126:129], v[142:145], v[164:167], v[126:129]
	v_mfma_f32_16x16x32_bf16 v[118:121], v[150:153], v[164:167], v[118:121]
	v_mfma_f32_16x16x32_bf16 v[110:113], v[142:145], v[172:175], v[110:113]
	v_mfma_f32_16x16x32_bf16 v[102:105], v[150:153], v[172:175], v[102:105]
	v_mfma_f32_16x16x32_bf16 v[94:97], v[142:145], v[180:183], v[94:97]
	v_mfma_f32_16x16x32_bf16 v[86:89], v[150:153], v[180:183], v[86:89]
	s_waitcnt lgkmcnt(0)
	v_mfma_f32_16x16x32_bf16 v[78:81], v[142:145], v[188:191], v[78:81]
	v_mfma_f32_16x16x32_bf16 v[70:73], v[150:153], v[188:191], v[70:73]
	s_setprio 0
	s_barrier
	s_add_i32 s66, 0, 0x1c000
	s_add_i32 s67, s68, s28
	v_add_u32_e32 v159, s66, v155
	v_lshl_add_u64 v[208:209], v[208:209], 0, s[86:87]
	s_mov_b32 m0, s67
	ds_read_b128 v[192:195], v159
	ds_read_b128 v[196:199], v159 offset:1024
	ds_read_b128 v[200:203], v159 offset:2048
	ds_read_b128 v[204:207], v159 offset:3072
	global_load_lds_dwordx4 v[208:209], off
	v_lshl_add_u64 v[208:209], v[210:211], 0, s[86:87]
	s_add_i32 m0, s67, 0x2000
	s_nop 0
	global_load_lds_dwordx4 v[208:209], off
	s_barrier
	s_setprio 1
	s_waitcnt lgkmcnt(3)
	v_mfma_f32_16x16x32_bf16 v[122:125], v[192:195], v[160:163], v[122:125]
	s_waitcnt lgkmcnt(1)
	v_mfma_f32_16x16x32_bf16 v[114:117], v[200:203], v[160:163], v[114:117]
	v_mfma_f32_16x16x32_bf16 v[106:109], v[192:195], v[168:171], v[106:109]
	v_mfma_f32_16x16x32_bf16 v[98:101], v[200:203], v[168:171], v[98:101]
	v_mfma_f32_16x16x32_bf16 v[90:93], v[192:195], v[176:179], v[90:93]
	v_mfma_f32_16x16x32_bf16 v[82:85], v[200:203], v[176:179], v[82:85]
	v_mfma_f32_16x16x32_bf16 v[74:77], v[192:195], v[184:187], v[74:77]
	v_mfma_f32_16x16x32_bf16 v[66:69], v[200:203], v[184:187], v[66:69]
	v_mfma_f32_16x16x32_bf16 v[122:125], v[196:199], v[164:167], v[122:125]
	s_waitcnt lgkmcnt(0)
	v_mfma_f32_16x16x32_bf16 v[114:117], v[204:207], v[164:167], v[114:117]
	v_mfma_f32_16x16x32_bf16 v[106:109], v[196:199], v[172:175], v[106:109]
	v_mfma_f32_16x16x32_bf16 v[98:101], v[204:207], v[172:175], v[98:101]
	v_mfma_f32_16x16x32_bf16 v[90:93], v[196:199], v[180:183], v[90:93]
	v_mfma_f32_16x16x32_bf16 v[82:85], v[204:207], v[180:183], v[82:85]
	v_mfma_f32_16x16x32_bf16 v[74:77], v[196:199], v[188:191], v[74:77]
	v_mfma_f32_16x16x32_bf16 v[66:69], v[204:207], v[188:191], v[66:69]
	s_setprio 0
	s_mov_b32 m0, s47
	v_lshl_add_u64 v[208:209], v[212:213], 0, s[86:87]
	s_barrier
	ds_read_b128 v[160:163], v158 offset:49152
	ds_read_b128 v[164:167], v158 offset:50176
	ds_read_b128 v[168:171], v158 offset:51200
	ds_read_b128 v[172:175], v158 offset:52224
	ds_read_b128 v[176:179], v158 offset:53248
	ds_read_b128 v[180:183], v158 offset:54272
	ds_read_b128 v[184:187], v158 offset:55296
	ds_read_b128 v[188:191], v158 offset:56320
	global_load_lds_dwordx4 v[208:209], off
	v_lshl_add_u64 v[208:209], v[214:215], 0, s[86:87]
	s_mov_b32 m0, s48
	s_nop 0
	global_load_lds_dwordx4 v[208:209], off
	s_barrier
; #define PG8_STAGE(bufoff, gbase, voff) do { _Pragma("unroll") for (int _i = 0; _i < 2; ++_i) \
;         __builtin_amdgcn_global_load_lds((const unsigned*)((const char*)(gbase) + (voff)[_i]), (LAS unsigned*)(lds + (bufoff) + ldsw + _i * 8192), 16, 0, 0); } while (0)
; #define PG8_MMA(ai, bj, At, Bt) do { __builtin_amdgcn_s_setprio(1); _Pragma("unroll") for (int m = 0; m < 4; ++m) _Pragma("unroll") for (int n = 0; n < 2; ++n) _Pragma("unroll") for (int k = 0; k < 2; ++k) \
;         acc[ai][bj][m][n] = __builtin_amdgcn_mfma_f32_16x16x32_bf16(Bt[n][k], At[m][k], acc[ai][bj][m][n], 0, 0, 0); __builtin_amdgcn_s_setprio(0); } while (0)
; #define PG8_WAIT_V(n) asm volatile("s_waitcnt vmcnt(" #n ")" ::: "memory")
; #define PG8_WAIT_L(n) asm volatile("s_waitcnt lgkmcnt(" #n ")" ::: "memory")
; #define PG8_BAR __builtin_amdgcn_s_barrier()
; #define PG8_SCHED __builtin_amdgcn_sched_barrier(0)
; template <class Epi>
; __device__ __forceinline__ void gemm_phase(const int tid, LAS unsigned char* lds, const Gemm g, const StaticOrder& S, const Epi& E) {
;     ...
;             PG8_BAR; PG8_WAIT_L(0); PG8_MMA(1, 0, At, B0); PG8_BAR; PG8_SCHED;
;             PG8_STAGE(PG8_SB(1, 1), b3 + hstep, voffB);
;             PG8_WAIT_V(6); PG8_BAR; PG8_STAGE(PG8_SA(1, 1), a3 + hstep, voffA);
;             PG8_MMA(1, 1, At, B1); PG8_BAR;
;         }
;         E(acc, cur, wr, wc, fr, fq, rsc);
	s_setprio 1
	s_waitcnt lgkmcnt(7)
	v_mfma_f32_16x16x32_bf16 v[62:65], v[130:133], v[160:163], v[62:65]
	v_mfma_f32_16x16x32_bf16 v[54:57], v[146:149], v[160:163], v[54:57]
	s_waitcnt lgkmcnt(5)
	v_mfma_f32_16x16x32_bf16 v[46:49], v[130:133], v[168:171], v[46:49]
	v_mfma_f32_16x16x32_bf16 v[38:41], v[146:149], v[168:171], v[38:41]
	s_waitcnt lgkmcnt(3)
	v_mfma_f32_16x16x32_bf16 v[30:33], v[130:133], v[176:179], v[30:33]
	v_mfma_f32_16x16x32_bf16 v[22:25], v[146:149], v[176:179], v[22:25]
	s_waitcnt lgkmcnt(1)
	v_mfma_f32_16x16x32_bf16 v[14:17], v[130:133], v[184:187], v[14:17]
	v_mfma_f32_16x16x32_bf16 v[6:9], v[146:149], v[184:187], v[6:9]
	v_mfma_f32_16x16x32_bf16 v[62:65], v[142:145], v[164:167], v[62:65]
	v_mfma_f32_16x16x32_bf16 v[54:57], v[150:153], v[164:167], v[54:57]
	v_mfma_f32_16x16x32_bf16 v[46:49], v[142:145], v[172:175], v[46:49]
	v_mfma_f32_16x16x32_bf16 v[38:41], v[150:153], v[172:175], v[38:41]
	v_mfma_f32_16x16x32_bf16 v[30:33], v[142:145], v[180:183], v[30:33]
	v_mfma_f32_16x16x32_bf16 v[22:25], v[150:153], v[180:183], v[22:25]
	s_waitcnt lgkmcnt(0)
	v_mfma_f32_16x16x32_bf16 v[14:17], v[142:145], v[188:191], v[14:17]
	v_mfma_f32_16x16x32_bf16 v[6:9], v[150:153], v[188:191], v[6:9]
	s_setprio 0
	s_barrier
	s_add_u32 s36, s36, 0x80080
	s_addc_u32 s37, s37, 0
	s_add_i32 s66, s66, s28
	v_lshl_add_u64 v[130:131], s[36:37], 0, v[0:1]
	s_mov_b32 m0, s66
	s_nop 0
	global_load_lds_dwordx4 v[130:131], off
	s_add_i32 m0, s66, 0x2000
	s_add_u32 s24, s24, 0x80080
	v_lshl_add_u64 v[130:131], s[36:37], 0, v[134:135]
	s_addc_u32 s25, s25, 0
	global_load_lds_dwordx4 v[130:131], off
	v_lshl_add_u64 v[130:131], s[24:25], 0, v[138:139]
	s_mov_b32 m0, s49
	s_waitcnt vmcnt(6)
	s_barrier
	global_load_lds_dwordx4 v[130:131], off
	v_lshl_add_u64 v[130:131], s[24:25], 0, v[136:137]
	s_mov_b32 m0, s50
	s_nop 0
	global_load_lds_dwordx4 v[130:131], off
	s_setprio 1
	v_mfma_f32_16x16x32_bf16 v[58:61], v[192:195], v[160:163], v[58:61]
	v_mfma_f32_16x16x32_bf16 v[50:53], v[200:203], v[160:163], v[50:53]
	v_mfma_f32_16x16x32_bf16 v[42:45], v[192:195], v[168:171], v[42:45]
	v_mfma_f32_16x16x32_bf16 v[34:37], v[200:203], v[168:171], v[34:37]
	v_mfma_f32_16x16x32_bf16 v[26:29], v[192:195], v[176:179], v[26:29]
	v_mfma_f32_16x16x32_bf16 v[18:21], v[200:203], v[176:179], v[18:21]
	v_mfma_f32_16x16x32_bf16 v[10:13], v[192:195], v[184:187], v[10:13]
	v_mfma_f32_16x16x32_bf16 v[2:5], v[200:203], v[184:187], v[2:5]
	v_mfma_f32_16x16x32_bf16 v[58:61], v[196:199], v[164:167], v[58:61]
	v_mfma_f32_16x16x32_bf16 v[50:53], v[204:207], v[164:167], v[50:53]
	v_mfma_f32_16x16x32_bf16 v[42:45], v[196:199], v[172:175], v[42:45]
	v_mfma_f32_16x16x32_bf16 v[34:37], v[204:207], v[172:175], v[34:37]
	v_mfma_f32_16x16x32_bf16 v[26:29], v[196:199], v[180:183], v[26:29]
	v_mfma_f32_16x16x32_bf16 v[18:21], v[204:207], v[180:183], v[18:21]
	v_mfma_f32_16x16x32_bf16 v[10:13], v[196:199], v[188:191], v[10:13]
	v_mfma_f32_16x16x32_bf16 v[2:5], v[204:207], v[188:191], v[2:5]
	s_setprio 0
	s_add_i32 s65, s65, 2
	s_add_u32 s59, s59, 0x100
	s_addc_u32 s60, s60, 0
	s_add_u32 s61, s61, 0x100
	s_addc_u32 s64, s64, 0
	s_cmp_gt_u32 s65, 29
	s_barrier
	s_cbranch_scc0 .LBB0_448
	v_lshl_add_u32 v150, s51, 8, v154
	s_cmp_lg_u32 s56, s51
	v_ashrrev_i32_e32 v151, 31, v150
	s_mov_b64 s[22:23], -1
	v_or_b32_e32 v148, 16, v150
	v_or_b32_e32 v146, 32, v150
	v_or_b32_e32 v144, 48, v150
	v_add_u32_e32 v152, 0x80, v150
	s_cbranch_scc0 .LBB0_453
; __device__ __forceinline__ void rows_rstd4(const float* ssqp, int rbase, int fq, float (&rs)[4]) {
;     f32x4 pa_[4], pb_[4];
; #pragma unroll
;     for (int m = 0; m < 4; ++m) { const float* q = ssqp + (size_t)(rbase + m * 16) * 32 + 8 * fq; pa_[m] = *(const f32x4*)q; pb_[m] = *(const f32x4*)(q + 4); }
;     asm volatile("" ::: "memory");
; #pragma unroll
;     for (int m = 0; m < 4; ++m) { const f32x4 a = pa_[m], b = pb_[m];
;         float t = ((a[0] + a[1]) + (a[2] + a[3])) + ((b[0] + b[1]) + (b[2] + b[3]));
;         t = xadd<16>(t); t = xadd<32>(t);
;         rs[m] = __builtin_amdgcn_rsqf(t * (1.0f / DM) + EPS); }
; }
;     __device__ __forceinline__ void operator()(const AccT& acc, const pg8::Unit& u, int wr, int wc, int fr, int fq, pg8::RsCache& rsc) const {
;         const int row0 = u.pm * 256 + wr * 64 + fr, col0 = u.pn * 128 + wc * 32 + 8 * fq;
;         if (rsc.pm != u.pm) {
;             float r0[4], r1[4]; rows_rstd4(ssq, row0, fq, r0); rows_rstd4(ssq, row0 + 128, fq, r1);
;             if (fq == 0) {
; #pragma unroll
;                 for (int m = 0; m < 4; ++m) { rsc.rl[m * 16 + fr] = r0[m]; rsc.rl[64 + m * 16 + fr] = r1[m]; } }
;             rsc.pm = u.pm; asm volatile("s_waitcnt lgkmcnt(0)" ::: "memory"); }
	v_lshlrev_b64 v[130:131], 7, v[150:151]
	v_lshl_add_u64 v[130:131], v[140:141], 0, v[130:131]
	global_load_dwordx4 v[160:163], v[130:131], off offset:16
	global_load_dwordx4 v[164:167], v[130:131], off
	v_ashrrev_i32_e32 v149, 31, v148
	v_lshlrev_b64 v[132:133], 7, v[148:149]
	v_lshl_add_u64 v[132:133], v[140:141], 0, v[132:133]
	global_load_dwordx4 v[168:171], v[132:133], off offset:16
	global_load_dwordx4 v[172:175], v[132:133], off
	v_ashrrev_i32_e32 v147, 31, v146
	v_lshlrev_b64 v[132:133], 7, v[146:147]
	v_lshl_add_u64 v[132:133], v[140:141], 0, v[132:133]
	global_load_dwordx4 v[176:179], v[132:133], off offset:16
	global_load_dwordx4 v[180:183], v[132:133], off
	v_ashrrev_i32_e32 v145, 31, v144
	v_lshlrev_b64 v[132:133], 7, v[144:145]
	v_lshl_add_u64 v[132:133], v[140:141], 0, v[132:133]
	global_load_dwordx4 v[184:187], v[132:133], off offset:16
	global_load_dwordx4 v[188:191], v[132:133], off
	s_movk_i32 s11, 0x4000
	s_mov_b64 s[22:23], 0x4800
	s_waitcnt vmcnt(0)
	v_add_f32_e32 v142, v162, v163
	v_add_f32_e32 v132, v164, v165
	v_add_f32_e32 v133, v166, v167
	v_add_f32_e32 v132, v132, v133
	v_add_f32_e32 v133, v160, v161
	v_add_f32_e32 v133, v133, v142
	v_add_f32_e32 v132, v132, v133
	ds_swizzle_b32 v133, v132 offset:swizzle(SWAP,16)
	v_add_f32_e32 v142, v170, v171
	s_waitcnt lgkmcnt(0)
	v_add_f32_e32 v151, v132, v133
	v_add_f32_e32 v132, v172, v173
	v_add_f32_e32 v133, v174, v175
	v_add_f32_e32 v132, v132, v133
	v_add_f32_e32 v133, v168, v169
	v_add_f32_e32 v133, v133, v142
	v_add_f32_e32 v132, v132, v133
	ds_swizzle_b32 v133, v132 offset:swizzle(SWAP,16)
	v_add_f32_e32 v142, v178, v179
	v_add_co_u32_e32 v174, vcc, s11, v130
	s_movk_i32 s11, 0x5000
	s_waitcnt lgkmcnt(0)
	v_add_f32_e32 v159, v132, v133
	v_add_f32_e32 v132, v180, v181
	v_add_f32_e32 v133, v182, v183
	v_add_f32_e32 v132, v132, v133
	v_add_f32_e32 v133, v176, v177
	v_add_f32_e32 v133, v133, v142
	v_add_f32_e32 v132, v132, v133
	ds_swizzle_b32 v133, v132 offset:swizzle(SWAP,16)
	v_add_f32_e32 v142, v186, v187
	v_addc_co_u32_e32 v175, vcc, 0, v131, vcc
	v_mov_b32_e32 v153, v151
	s_waitcnt lgkmcnt(0)
	v_add_f32_e32 v161, v132, v133
	v_add_f32_e32 v132, v188, v189
	v_add_f32_e32 v133, v190, v191
	v_add_f32_e32 v132, v132, v133
	v_add_f32_e32 v133, v184, v185
	v_add_f32_e32 v133, v133, v142
	v_add_f32_e32 v132, v132, v133
	ds_swizzle_b32 v133, v132 offset:swizzle(SWAP,16)
	v_add_u32_e32 v142, 0x80, v150
	v_ashrrev_i32_e32 v143, 31, v142
	v_add_co_u32_e32 v190, vcc, s11, v130
	s_waitcnt lgkmcnt(0)
	v_add_f32_e32 v163, v132, v133
	v_lshlrev_b64 v[132:133], 7, v[142:143]
	v_lshl_add_u64 v[132:133], v[140:141], 0, v[132:133]
	global_load_dwordx4 v[166:169], v[132:133], off offset:16
	global_load_dwordx4 v[170:173], v[132:133], off
	v_lshl_add_u64 v[132:133], v[130:131], 0, s[22:23]
	global_load_dwordx4 v[174:177], v[174:175], off offset:2048
	s_nop 0
	global_load_dwordx4 v[178:181], v[132:133], off offset:16
	s_mov_b64 s[22:23], 0x5000
	v_lshl_add_u64 v[132:133], v[130:131], 0, s[22:23]
	v_addc_co_u32_e32 v191, vcc, 0, v131, vcc
	s_mov_b64 s[22:23], 0x5800
	global_load_dwordx4 v[182:185], v[190:191], off
	global_load_dwordx4 v[186:189], v[132:133], off offset:16
	v_lshl_add_u64 v[130:131], v[130:131], 0, s[22:23]
	global_load_dwordx4 v[190:193], v[190:191], off offset:2048
	s_nop 0
	global_load_dwordx4 v[130:133], v[130:131], off offset:16
	v_mov_b32_e32 v160, v159
	v_mov_b32_e32 v162, v161
	v_mov_b32_e32 v164, v163
	v_permlane32_swap_b32_e32 v151, v153
	v_permlane32_swap_b32_e32 v159, v160
	v_permlane32_swap_b32_e32 v161, v162
	v_permlane32_swap_b32_e32 v163, v164
	s_waitcnt vmcnt(7)
	v_add_f32_e32 v166, v166, v167
	v_add_f32_e32 v167, v168, v169
	v_add_f32_e32 v166, v166, v167
	s_waitcnt vmcnt(5)
	v_add_f32_e32 v167, v174, v175
	v_add_f32_e32 v168, v176, v177
	v_add_f32_e32 v165, v170, v171
	v_add_f32_e32 v170, v172, v173
	v_add_f32_e32 v167, v167, v168
	s_waitcnt vmcnt(4)
	v_add_f32_e32 v168, v178, v179
	v_add_f32_e32 v169, v180, v181
	v_add_f32_e32 v165, v165, v170
	v_add_f32_e32 v168, v168, v169
	s_waitcnt vmcnt(3)
	v_add_f32_e32 v169, v182, v183
	v_add_f32_e32 v170, v184, v185
	v_add_f32_e32 v169, v169, v170
	s_waitcnt vmcnt(2)
	v_add_f32_e32 v170, v186, v187
	v_add_f32_e32 v171, v188, v189
	v_add_f32_e32 v170, v170, v171
	s_waitcnt vmcnt(1)
	v_add_f32_e32 v171, v190, v191
	v_add_f32_e32 v172, v192, v193
	s_waitcnt vmcnt(0)
	v_add_f32_e32 v130, v130, v131
	v_add_f32_e32 v131, v132, v133
	v_add_f32_e32 v171, v171, v172
	v_add_f32_e32 v130, v130, v131
	v_add_f32_e32 v165, v165, v166
	v_add_f32_e32 v167, v167, v168
	v_add_f32_e32 v169, v169, v170
	v_add_f32_e32 v130, v171, v130
	ds_swizzle_b32 v166, v165 offset:swizzle(SWAP,16)
	ds_swizzle_b32 v168, v167 offset:swizzle(SWAP,16)
	ds_swizzle_b32 v170, v169 offset:swizzle(SWAP,16)
	ds_swizzle_b32 v131, v130 offset:swizzle(SWAP,16)
	s_waitcnt lgkmcnt(3)
	v_add_f32_e32 v165, v165, v166
	s_waitcnt lgkmcnt(2)
	v_add_f32_e32 v167, v167, v168
	s_waitcnt lgkmcnt(1)
	v_add_f32_e32 v169, v169, v170
	s_waitcnt lgkmcnt(0)
	v_add_f32_e32 v130, v130, v131
	v_mov_b32_e32 v166, v165
	v_mov_b32_e32 v168, v167
	v_mov_b32_e32 v170, v169
	v_mov_b32_e32 v131, v130
	v_permlane32_swap_b32_e32 v165, v166
	v_permlane32_swap_b32_e32 v167, v168
	v_permlane32_swap_b32_e32 v169, v170
	v_permlane32_swap_b32_e32 v130, v131
	s_and_saveexec_b64 s[22:23], s[4:5]
	s_cbranch_execz .LBB0_452
	v_add_f32_e32 v159, v159, v160
	v_add_f32_e32 v151, v151, v153
	v_add_f32_e32 v132, v167, v168
	v_add_f32_e32 v133, v165, v166
	v_fmamk_f32 v159, v159, 0x3a000000, v242
	v_fmamk_f32 v151, v151, 0x3a000000, v242
	v_fmamk_f32 v132, v132, 0x3a000000, v242
	v_fmamk_f32 v133, v133, 0x3a000000, v242
	v_add_f32_e32 v163, v163, v164
	v_add_f32_e32 v161, v161, v162
	v_rsq_f32_e32 v159, v159
	v_rsq_f32_e32 v151, v151
	v_add_f32_e32 v130, v130, v131
	v_add_f32_e32 v131, v169, v170
	v_rsq_f32_e32 v132, v132
	v_rsq_f32_e32 v133, v133
	v_fmamk_f32 v163, v163, 0x3a000000, v242
	v_fmamk_f32 v153, v161, 0x3a000000, v242
	v_fmamk_f32 v130, v130, 0x3a000000, v242
	v_fmamk_f32 v131, v131, 0x3a000000, v242
	v_rsq_f32_e32 v163, v163
	v_rsq_f32_e32 v153, v153
	v_rsq_f32_e32 v130, v130
	v_rsq_f32_e32 v131, v131
	ds_write2_b32 v156, v151, v159 offset1:16
	ds_write2_b32 v156, v133, v132 offset0:64 offset1:80
	ds_write2_b32 v156, v153, v163 offset0:32 offset1:48
	ds_write2_b32 v156, v131, v130 offset0:96 offset1:112

; __device__ __forceinline__ void convert_tile(const int tid, float* lt, const float* src0, const float* src1, const float* gain, bf16_t* dst, int K, int Nsrc, int mode, int tile) {
;     ...
;     for (int i = 0; i < 8; ++i) { v[i] = (f32x4){0.f, 0.f, 0.f, 0.f}; if (col >= 0) v[i] = *(const f32x4*)(sp + (size_t)(k0 + kr + 8 * i) * Nsrc + col); }
;     if (gain) {
; #pragma unroll
;         for (int i = 0; i < 8; ++i) v[i] *= gain[k0 + kr + 8 * i]; }
.LBB0_489:
	v_ashrrev_i32_e32 v39, 31, v38
	v_lshl_add_u64 v[2:3], v[38:39], 2, s[8:9]
	global_load_dword v0, v[2:3], off
	global_load_dword v56, v[2:3], off offset:32
	global_load_dword v58, v[2:3], off offset:64
	global_load_dword v60, v[2:3], off offset:96
	global_load_dword v62, v[2:3], off offset:128
	global_load_dword v64, v[2:3], off offset:160
	global_load_dword v66, v[2:3], off offset:192
	s_nop 0
	global_load_dword v2, v[2:3], off offset:224
	s_waitcnt vmcnt(0)
	v_pk_mul_f32 v[6:7], v[6:7], v[0:1] op_sel_hi:[1,0]
	v_pk_mul_f32 v[4:5], v[4:5], v[0:1] op_sel_hi:[1,0]
	v_pk_mul_f32 v[10:11], v[10:11], v[56:57] op_sel_hi:[1,0]
	v_pk_mul_f32 v[8:9], v[8:9], v[56:57] op_sel_hi:[1,0]
	v_pk_mul_f32 v[14:15], v[14:15], v[58:59] op_sel_hi:[1,0]
	v_pk_mul_f32 v[12:13], v[12:13], v[58:59] op_sel_hi:[1,0]
	v_pk_mul_f32 v[18:19], v[18:19], v[60:61] op_sel_hi:[1,0]
	v_pk_mul_f32 v[16:17], v[16:17], v[60:61] op_sel_hi:[1,0]
	v_pk_mul_f32 v[22:23], v[22:23], v[62:63] op_sel_hi:[1,0]
	v_pk_mul_f32 v[20:21], v[20:21], v[62:63] op_sel_hi:[1,0]
	v_pk_mul_f32 v[26:27], v[26:27], v[64:65] op_sel_hi:[1,0]
	v_pk_mul_f32 v[24:25], v[24:25], v[64:65] op_sel_hi:[1,0]
	v_pk_mul_f32 v[30:31], v[30:31], v[66:67] op_sel_hi:[1,0]
	v_pk_mul_f32 v[28:29], v[28:29], v[66:67] op_sel_hi:[1,0]
	v_pk_mul_f32 v[34:35], v[34:35], v[2:3] op_sel_hi:[1,0]
	v_pk_mul_f32 v[32:33], v[32:33], v[2:3] op_sel_hi:[1,0]
	s_branch .LBB0_461

; __device__ __forceinline__ void convert_tile(const int tid, float* lt, const float* src0, const float* src1, const float* gain, bf16_t* dst, int K, int Nsrc, int mode, int tile) {
;     ...
;     for (int i = 0; i < 8; ++i) { v[i] = (f32x4){0.f, 0.f, 0.f, 0.f}; if (col >= 0) v[i] = *(const f32x4*)(sp + (size_t)(k0 + kr + 8 * i) * Nsrc + col); }
;     if (gain) {
; #pragma unroll
;         for (int i = 0; i < 8; ++i) v[i] *= gain[k0 + kr + 8 * i]; }
.LBB0_530:
	s_or_b64 exec, exec, s[14:15]
	s_and_b64 vcc, exec, s[10:11]
	s_cbranch_vccz .LBB0_493
	v_ashrrev_i32_e32 v39, 31, v38
	v_lshl_add_u64 v[2:3], v[38:39], 2, s[8:9]
	global_load_dword v0, v[2:3], off
	global_load_dword v56, v[2:3], off offset:32
	global_load_dword v58, v[2:3], off offset:64
	global_load_dword v60, v[2:3], off offset:96
	global_load_dword v62, v[2:3], off offset:128
	global_load_dword v64, v[2:3], off offset:160
	global_load_dword v66, v[2:3], off offset:192
	s_nop 0
	global_load_dword v2, v[2:3], off offset:224
	s_waitcnt vmcnt(0)
	v_pk_mul_f32 v[6:7], v[6:7], v[0:1] op_sel_hi:[1,0]
	v_pk_mul_f32 v[4:5], v[4:5], v[0:1] op_sel_hi:[1,0]
	v_pk_mul_f32 v[10:11], v[10:11], v[56:57] op_sel_hi:[1,0]
	v_pk_mul_f32 v[8:9], v[8:9], v[56:57] op_sel_hi:[1,0]
	v_pk_mul_f32 v[14:15], v[14:15], v[58:59] op_sel_hi:[1,0]
	v_pk_mul_f32 v[12:13], v[12:13], v[58:59] op_sel_hi:[1,0]
	v_pk_mul_f32 v[18:19], v[18:19], v[60:61] op_sel_hi:[1,0]
	v_pk_mul_f32 v[16:17], v[16:17], v[60:61] op_sel_hi:[1,0]
	v_pk_mul_f32 v[22:23], v[22:23], v[62:63] op_sel_hi:[1,0]
	v_pk_mul_f32 v[20:21], v[20:21], v[62:63] op_sel_hi:[1,0]
	v_pk_mul_f32 v[26:27], v[26:27], v[64:65] op_sel_hi:[1,0]
	v_pk_mul_f32 v[24:25], v[24:25], v[64:65] op_sel_hi:[1,0]
	v_pk_mul_f32 v[30:31], v[30:31], v[66:67] op_sel_hi:[1,0]
	v_pk_mul_f32 v[28:29], v[28:29], v[66:67] op_sel_hi:[1,0]
	v_pk_mul_f32 v[34:35], v[34:35], v[2:3] op_sel_hi:[1,0]
	v_pk_mul_f32 v[32:33], v[32:33], v[2:3] op_sel_hi:[1,0]
	s_branch .LBB0_493
